# E56b: GEMM K-loops: first 16 of 32 MFMAs of each compute segment issued before the opening barrier (half-segment overlap of the two wave halves); on E41
# baseline (speedup 1.0000x reference)
.LBB0_202:
	ds_read_b128 v[146:149], v157
	ds_read_b128 v[150:153], v157 offset:1024
	ds_read_b128 v[164:167], v157 offset:2048
	ds_read_b128 v[168:171], v157 offset:3072
	ds_read_b128 v[172:175], v158
	ds_read_b128 v[176:179], v158 offset:1024
	ds_read_b128 v[180:183], v158 offset:2048
	ds_read_b128 v[184:187], v158 offset:3072
	s_add_u32 s72, s76, 0xfffc0080
	s_addc_u32 s73, s77, -1
	s_cmp_eq_u32 s71, 12
	s_cselect_b32 s85, s5, s73
	s_cselect_b32 s84, s43, s72
	s_cselect_b32 s79, s41, s70
	s_cselect_b32 s78, s49, s69
	v_lshl_add_u64 v[188:189], s[76:77], 0, v[138:139]
	s_add_i32 m0, s93, 0xc000
	ds_read_b128 v[192:195], v159
	ds_read_b128 v[196:199], v159 offset:1024
	ds_read_b128 v[200:203], v159 offset:2048
	ds_read_b128 v[204:207], v159 offset:3072
	ds_read_b128 v[208:211], v159 offset:4096
	ds_read_b128 v[218:221], v159 offset:5120
	ds_read_b128 v[224:227], v159 offset:6144
	ds_read_b128 v[228:231], v159 offset:7168
	global_load_lds_dwordx4 v[188:189], off
	v_lshl_add_u64 v[188:189], s[76:77], 0, v[140:141]
	s_add_i32 m0, s93, 0xe000
	s_nop 0
	global_load_lds_dwordx4 v[188:189], off
	s_waitcnt vmcnt(8)
	s_waitcnt lgkmcnt(0)
	v_mfma_f32_16x16x32_bf16 v[126:129], v[146:149], v[192:195], v[126:129]
	v_mfma_f32_16x16x32_bf16 v[122:125], v[164:167], v[192:195], v[122:125]
	v_mfma_f32_16x16x32_bf16 v[110:113], v[146:149], v[200:203], v[110:113]
	v_mfma_f32_16x16x32_bf16 v[106:109], v[164:167], v[200:203], v[106:109]
	v_mfma_f32_16x16x32_bf16 v[94:97], v[146:149], v[208:211], v[94:97]
	v_mfma_f32_16x16x32_bf16 v[90:93], v[164:167], v[208:211], v[90:93]
	v_mfma_f32_16x16x32_bf16 v[78:81], v[146:149], v[224:227], v[78:81]
	v_mfma_f32_16x16x32_bf16 v[74:77], v[164:167], v[224:227], v[74:77]
	v_mfma_f32_16x16x32_bf16 v[126:129], v[150:153], v[196:199], v[126:129]
	v_mfma_f32_16x16x32_bf16 v[122:125], v[168:171], v[196:199], v[122:125]
	v_mfma_f32_16x16x32_bf16 v[110:113], v[150:153], v[204:207], v[110:113]
	v_mfma_f32_16x16x32_bf16 v[106:109], v[168:171], v[204:207], v[106:109]
	v_mfma_f32_16x16x32_bf16 v[94:97], v[150:153], v[218:221], v[94:97]
	v_mfma_f32_16x16x32_bf16 v[90:93], v[168:171], v[218:221], v[90:93]
	v_mfma_f32_16x16x32_bf16 v[78:81], v[150:153], v[228:231], v[78:81]
	v_mfma_f32_16x16x32_bf16 v[74:77], v[168:171], v[228:231], v[74:77]
	s_barrier
	s_setprio 1
	s_waitcnt lgkmcnt(0)
	v_mfma_f32_16x16x32_bf16 v[118:121], v[172:175], v[192:195], v[118:121]
	v_mfma_f32_16x16x32_bf16 v[114:117], v[180:183], v[192:195], v[114:117]
	v_mfma_f32_16x16x32_bf16 v[102:105], v[172:175], v[200:203], v[102:105]
	v_mfma_f32_16x16x32_bf16 v[98:101], v[180:183], v[200:203], v[98:101]
	v_mfma_f32_16x16x32_bf16 v[86:89], v[172:175], v[208:211], v[86:89]
	v_mfma_f32_16x16x32_bf16 v[82:85], v[180:183], v[208:211], v[82:85]
	v_mfma_f32_16x16x32_bf16 v[70:73], v[172:175], v[224:227], v[70:73]
	v_mfma_f32_16x16x32_bf16 v[66:69], v[180:183], v[224:227], v[66:69]
	v_mfma_f32_16x16x32_bf16 v[118:121], v[176:179], v[196:199], v[118:121]
	v_mfma_f32_16x16x32_bf16 v[114:117], v[184:187], v[196:199], v[114:117]
	v_mfma_f32_16x16x32_bf16 v[102:105], v[176:179], v[204:207], v[102:105]
	v_mfma_f32_16x16x32_bf16 v[98:101], v[184:187], v[204:207], v[98:101]
	v_mfma_f32_16x16x32_bf16 v[86:89], v[176:179], v[218:221], v[86:89]
	v_mfma_f32_16x16x32_bf16 v[82:85], v[184:187], v[218:221], v[82:85]
	v_mfma_f32_16x16x32_bf16 v[70:73], v[176:179], v[228:231], v[70:73]
	v_mfma_f32_16x16x32_bf16 v[66:69], v[184:187], v[228:231], v[66:69]
	s_setprio 0
	s_barrier
	s_add_i32 s72, s67, s92
	v_lshl_add_u64 v[188:189], s[78:79], 0, v[132:133]
	s_mov_b32 m0, s72
	ds_read_b128 v[192:195], v159 offset:16384
	ds_read_b128 v[196:199], v159 offset:17408
	ds_read_b128 v[200:203], v159 offset:18432
	ds_read_b128 v[204:207], v159 offset:19456
	ds_read_b128 v[208:211], v159 offset:20480
	ds_read_b128 v[218:221], v159 offset:21504
	ds_read_b128 v[224:227], v159 offset:22528
	ds_read_b128 v[228:231], v159 offset:23552
	global_load_lds_dwordx4 v[188:189], off
	s_add_i32 m0, s72, 0x2000
	s_add_u32 s72, s78, 0x40000
	v_lshl_add_u64 v[214:215], s[78:79], 0, v[136:137]
	s_addc_u32 s73, s79, 0
	s_add_i32 s74, s68, s92
	global_load_lds_dwordx4 v[214:215], off
	v_lshl_add_u64 v[232:233], s[72:73], 0, v[132:133]
	s_mov_b32 m0, s74
	v_lshl_add_u64 v[234:235], s[84:85], 0, v[134:135]
	global_load_lds_dwordx4 v[232:233], off
	v_lshl_add_u64 v[232:233], s[72:73], 0, v[136:137]
	s_add_i32 m0, s74, 0x2000
	s_nop 0
	global_load_lds_dwordx4 v[232:233], off
	v_lshl_add_u64 v[232:233], s[84:85], 0, v[130:131]
	s_mov_b32 m0, s93
	s_nop 0
	global_load_lds_dwordx4 v[232:233], off
	s_mov_b32 m0, s94
	s_nop 0
	global_load_lds_dwordx4 v[234:235], off
	s_waitcnt vmcnt(8)
	s_waitcnt lgkmcnt(0)
	v_mfma_f32_16x16x32_bf16 v[62:65], v[146:149], v[192:195], v[62:65]
	v_mfma_f32_16x16x32_bf16 v[58:61], v[164:167], v[192:195], v[58:61]
	v_mfma_f32_16x16x32_bf16 v[46:49], v[146:149], v[200:203], v[46:49]
	v_mfma_f32_16x16x32_bf16 v[42:45], v[164:167], v[200:203], v[42:45]
	v_mfma_f32_16x16x32_bf16 v[30:33], v[146:149], v[208:211], v[30:33]
	v_mfma_f32_16x16x32_bf16 v[26:29], v[164:167], v[208:211], v[26:29]
	v_mfma_f32_16x16x32_bf16 v[14:17], v[146:149], v[224:227], v[14:17]
	v_mfma_f32_16x16x32_bf16 v[10:13], v[164:167], v[224:227], v[10:13]
	v_mfma_f32_16x16x32_bf16 v[62:65], v[150:153], v[196:199], v[62:65]
	v_mfma_f32_16x16x32_bf16 v[58:61], v[168:171], v[196:199], v[58:61]
	v_mfma_f32_16x16x32_bf16 v[46:49], v[150:153], v[204:207], v[46:49]
	v_mfma_f32_16x16x32_bf16 v[42:45], v[168:171], v[204:207], v[42:45]
	v_mfma_f32_16x16x32_bf16 v[30:33], v[150:153], v[218:221], v[30:33]
	v_mfma_f32_16x16x32_bf16 v[26:29], v[168:171], v[218:221], v[26:29]
	v_mfma_f32_16x16x32_bf16 v[14:17], v[150:153], v[228:231], v[14:17]
	v_mfma_f32_16x16x32_bf16 v[10:13], v[168:171], v[228:231], v[10:13]
	s_barrier
	s_setprio 1
	s_waitcnt lgkmcnt(0)
	v_mfma_f32_16x16x32_bf16 v[54:57], v[172:175], v[192:195], v[54:57]
	v_mfma_f32_16x16x32_bf16 v[50:53], v[180:183], v[192:195], v[50:53]
	v_mfma_f32_16x16x32_bf16 v[38:41], v[172:175], v[200:203], v[38:41]
	v_mfma_f32_16x16x32_bf16 v[34:37], v[180:183], v[200:203], v[34:37]
	v_mfma_f32_16x16x32_bf16 v[22:25], v[172:175], v[208:211], v[22:25]
	v_mfma_f32_16x16x32_bf16 v[18:21], v[180:183], v[208:211], v[18:21]
	v_mfma_f32_16x16x32_bf16 v[6:9], v[172:175], v[224:227], v[6:9]
	v_mfma_f32_16x16x32_bf16 v[2:5], v[180:183], v[224:227], v[2:5]
	v_mfma_f32_16x16x32_bf16 v[54:57], v[176:179], v[196:199], v[54:57]
	v_mfma_f32_16x16x32_bf16 v[50:53], v[184:187], v[196:199], v[50:53]
	v_mfma_f32_16x16x32_bf16 v[38:41], v[176:179], v[204:207], v[38:41]
	v_mfma_f32_16x16x32_bf16 v[34:37], v[184:187], v[204:207], v[34:37]
	v_mfma_f32_16x16x32_bf16 v[22:25], v[176:179], v[218:221], v[22:25]
	v_mfma_f32_16x16x32_bf16 v[18:21], v[184:187], v[218:221], v[18:21]
	v_mfma_f32_16x16x32_bf16 v[6:9], v[176:179], v[228:231], v[6:9]
	v_mfma_f32_16x16x32_bf16 v[2:5], v[184:187], v[228:231], v[2:5]
	s_setprio 0
	s_barrier
	s_add_i32 s74, 0, 0x18000
	v_add_u32_e32 v161, s74, v155
	s_add_i32 s75, 0, 0x1c000
	ds_read_b128 v[146:149], v161
	ds_read_b128 v[150:153], v161 offset:1024
	ds_read_b128 v[164:167], v161 offset:2048
	ds_read_b128 v[168:171], v161 offset:3072
	v_add_u32_e32 v161, s75, v155
	ds_read_b128 v[172:175], v161
	ds_read_b128 v[176:179], v161 offset:1024
	ds_read_b128 v[180:183], v161 offset:2048
	ds_read_b128 v[184:187], v161 offset:3072
	s_add_u32 s72, s84, 0x40000
	s_addc_u32 s73, s85, 0
	s_mov_b32 m0, s95
	v_lshl_add_u64 v[236:237], s[72:73], 0, v[130:131]
	ds_read_b128 v[192:195], v159 offset:32768
	ds_read_b128 v[196:199], v159 offset:33792
	ds_read_b128 v[200:203], v159 offset:34816
	ds_read_b128 v[204:207], v159 offset:35840
	ds_read_b128 v[208:211], v159 offset:36864
	ds_read_b128 v[218:221], v159 offset:37888
	ds_read_b128 v[224:227], v159 offset:38912
	ds_read_b128 v[228:231], v159 offset:39936
	global_load_lds_dwordx4 v[236:237], off
	v_lshl_add_u64 v[236:237], s[72:73], 0, v[134:135]
	s_mov_b32 m0, s96
	s_nop 0
	global_load_lds_dwordx4 v[236:237], off
	s_waitcnt vmcnt(8)
	s_waitcnt lgkmcnt(0)
	v_mfma_f32_16x16x32_bf16 v[126:129], v[146:149], v[192:195], v[126:129]
	v_mfma_f32_16x16x32_bf16 v[122:125], v[164:167], v[192:195], v[122:125]
	v_mfma_f32_16x16x32_bf16 v[110:113], v[146:149], v[200:203], v[110:113]
	v_mfma_f32_16x16x32_bf16 v[106:109], v[164:167], v[200:203], v[106:109]
	v_mfma_f32_16x16x32_bf16 v[94:97], v[146:149], v[208:211], v[94:97]
	v_mfma_f32_16x16x32_bf16 v[90:93], v[164:167], v[208:211], v[90:93]
	v_mfma_f32_16x16x32_bf16 v[78:81], v[146:149], v[224:227], v[78:81]
	v_mfma_f32_16x16x32_bf16 v[74:77], v[164:167], v[224:227], v[74:77]
	v_mfma_f32_16x16x32_bf16 v[126:129], v[150:153], v[196:199], v[126:129]
	v_mfma_f32_16x16x32_bf16 v[122:125], v[168:171], v[196:199], v[122:125]
	v_mfma_f32_16x16x32_bf16 v[110:113], v[150:153], v[204:207], v[110:113]
	v_mfma_f32_16x16x32_bf16 v[106:109], v[168:171], v[204:207], v[106:109]
	v_mfma_f32_16x16x32_bf16 v[94:97], v[150:153], v[218:221], v[94:97]
	v_mfma_f32_16x16x32_bf16 v[90:93], v[168:171], v[218:221], v[90:93]
	v_mfma_f32_16x16x32_bf16 v[78:81], v[150:153], v[228:231], v[78:81]
	v_mfma_f32_16x16x32_bf16 v[74:77], v[168:171], v[228:231], v[74:77]
	s_barrier
	s_setprio 1
	s_waitcnt lgkmcnt(0)
	v_mfma_f32_16x16x32_bf16 v[118:121], v[172:175], v[192:195], v[118:121]
	v_mfma_f32_16x16x32_bf16 v[114:117], v[180:183], v[192:195], v[114:117]
	v_mfma_f32_16x16x32_bf16 v[102:105], v[172:175], v[200:203], v[102:105]
	v_mfma_f32_16x16x32_bf16 v[98:101], v[180:183], v[200:203], v[98:101]
	v_mfma_f32_16x16x32_bf16 v[86:89], v[172:175], v[208:211], v[86:89]
	v_mfma_f32_16x16x32_bf16 v[82:85], v[180:183], v[208:211], v[82:85]
	v_mfma_f32_16x16x32_bf16 v[70:73], v[172:175], v[224:227], v[70:73]
	v_mfma_f32_16x16x32_bf16 v[66:69], v[180:183], v[224:227], v[66:69]
	v_mfma_f32_16x16x32_bf16 v[118:121], v[176:179], v[196:199], v[118:121]
	v_mfma_f32_16x16x32_bf16 v[114:117], v[184:187], v[196:199], v[114:117]
	v_mfma_f32_16x16x32_bf16 v[102:105], v[176:179], v[204:207], v[102:105]
	v_mfma_f32_16x16x32_bf16 v[98:101], v[184:187], v[204:207], v[98:101]
	v_mfma_f32_16x16x32_bf16 v[86:89], v[176:179], v[218:221], v[86:89]
	v_mfma_f32_16x16x32_bf16 v[82:85], v[184:187], v[218:221], v[82:85]
	v_mfma_f32_16x16x32_bf16 v[70:73], v[176:179], v[228:231], v[70:73]
	v_mfma_f32_16x16x32_bf16 v[66:69], v[184:187], v[228:231], v[66:69]
	s_setprio 0
	s_barrier
	s_add_i32 s72, s74, s92
	v_lshl_add_u64 v[188:189], v[188:189], 0, s[36:37]
	s_mov_b32 m0, s72
	ds_read_b128 v[192:195], v159 offset:49152
	ds_read_b128 v[196:199], v159 offset:50176
	ds_read_b128 v[200:203], v159 offset:51200
	ds_read_b128 v[204:207], v159 offset:52224
	ds_read_b128 v[208:211], v159 offset:53248
	ds_read_b128 v[218:221], v159 offset:54272
	ds_read_b128 v[224:227], v159 offset:55296
	ds_read_b128 v[228:231], v159 offset:56320
	global_load_lds_dwordx4 v[188:189], off
	s_add_i32 m0, s72, 0x2000
	s_add_u32 s72, s78, 0x40080
	v_lshl_add_u64 v[188:189], v[214:215], 0, s[36:37]
	s_addc_u32 s73, s79, 0
	s_add_i32 s74, s75, s92
	global_load_lds_dwordx4 v[188:189], off
	v_lshl_add_u64 v[188:189], s[72:73], 0, v[132:133]
	s_mov_b32 m0, s74
	s_nop 0
	global_load_lds_dwordx4 v[188:189], off
	v_lshl_add_u64 v[188:189], s[72:73], 0, v[136:137]
	s_add_i32 m0, s74, 0x2000
	s_nop 0
	global_load_lds_dwordx4 v[188:189], off
	v_lshl_add_u64 v[188:189], v[232:233], 0, s[36:37]
	s_mov_b32 m0, s86
	s_nop 0
	global_load_lds_dwordx4 v[188:189], off
	v_lshl_add_u64 v[188:189], v[234:235], 0, s[36:37]
	s_mov_b32 m0, s87
	s_nop 0
	global_load_lds_dwordx4 v[188:189], off
	s_waitcnt vmcnt(8)
	s_waitcnt lgkmcnt(0)
	v_mfma_f32_16x16x32_bf16 v[62:65], v[146:149], v[192:195], v[62:65]
	v_mfma_f32_16x16x32_bf16 v[58:61], v[164:167], v[192:195], v[58:61]
	v_mfma_f32_16x16x32_bf16 v[46:49], v[146:149], v[200:203], v[46:49]
	v_mfma_f32_16x16x32_bf16 v[42:45], v[164:167], v[200:203], v[42:45]
	v_mfma_f32_16x16x32_bf16 v[30:33], v[146:149], v[208:211], v[30:33]
	v_mfma_f32_16x16x32_bf16 v[26:29], v[164:167], v[208:211], v[26:29]
	v_mfma_f32_16x16x32_bf16 v[14:17], v[146:149], v[224:227], v[14:17]
	v_mfma_f32_16x16x32_bf16 v[10:13], v[164:167], v[224:227], v[10:13]
	v_mfma_f32_16x16x32_bf16 v[62:65], v[150:153], v[196:199], v[62:65]
	v_mfma_f32_16x16x32_bf16 v[58:61], v[168:171], v[196:199], v[58:61]
	v_mfma_f32_16x16x32_bf16 v[46:49], v[150:153], v[204:207], v[46:49]
	v_mfma_f32_16x16x32_bf16 v[42:45], v[168:171], v[204:207], v[42:45]
	v_mfma_f32_16x16x32_bf16 v[30:33], v[150:153], v[218:221], v[30:33]
	v_mfma_f32_16x16x32_bf16 v[26:29], v[168:171], v[218:221], v[26:29]
	v_mfma_f32_16x16x32_bf16 v[14:17], v[150:153], v[228:231], v[14:17]
	v_mfma_f32_16x16x32_bf16 v[10:13], v[168:171], v[228:231], v[10:13]
	s_barrier
	s_setprio 1
	s_waitcnt lgkmcnt(0)
	v_mfma_f32_16x16x32_bf16 v[54:57], v[172:175], v[192:195], v[54:57]
	v_mfma_f32_16x16x32_bf16 v[50:53], v[180:183], v[192:195], v[50:53]
	v_mfma_f32_16x16x32_bf16 v[38:41], v[172:175], v[200:203], v[38:41]
	v_mfma_f32_16x16x32_bf16 v[34:37], v[180:183], v[200:203], v[34:37]
	v_mfma_f32_16x16x32_bf16 v[22:25], v[172:175], v[208:211], v[22:25]
	v_mfma_f32_16x16x32_bf16 v[18:21], v[180:183], v[208:211], v[18:21]
	v_mfma_f32_16x16x32_bf16 v[6:9], v[172:175], v[224:227], v[6:9]
	v_mfma_f32_16x16x32_bf16 v[2:5], v[180:183], v[224:227], v[2:5]
	v_mfma_f32_16x16x32_bf16 v[54:57], v[176:179], v[196:199], v[54:57]
	v_mfma_f32_16x16x32_bf16 v[50:53], v[184:187], v[196:199], v[50:53]
	v_mfma_f32_16x16x32_bf16 v[38:41], v[176:179], v[204:207], v[38:41]
	v_mfma_f32_16x16x32_bf16 v[34:37], v[184:187], v[204:207], v[34:37]
	v_mfma_f32_16x16x32_bf16 v[22:25], v[176:179], v[218:221], v[22:25]
	v_mfma_f32_16x16x32_bf16 v[18:21], v[184:187], v[218:221], v[18:21]
	v_mfma_f32_16x16x32_bf16 v[6:9], v[176:179], v[228:231], v[6:9]
	v_mfma_f32_16x16x32_bf16 v[2:5], v[184:187], v[228:231], v[2:5]
	s_setprio 0
	s_barrier
	s_add_i32 s71, s71, 2
	s_add_u32 s76, s76, 0x100
	s_addc_u32 s77, s77, 0
	s_add_u32 s69, s69, 0x100
	s_addc_u32 s70, s70, 0
	s_cmp_gt_u32 s71, 13
	s_cbranch_scc0 .LBB0_202
	s_and_b64 vcc, exec, s[38:39]
	s_cbranch_vccz .LBB0_205
	s_barrier

.LBB0_679:
	v_add_u32_e32 v168, s47, v153
	v_add_u32_e32 v184, s48, v153
	s_add_u32 s30, s16, s28
	ds_read_b128 v[156:159], v168
	ds_read_b128 v[160:163], v168 offset:1024
	ds_read_b128 v[164:167], v168 offset:2048
	ds_read_b128 v[168:171], v168 offset:3072
	ds_read_b128 v[172:175], v184
	ds_read_b128 v[176:179], v184 offset:1024
	ds_read_b128 v[180:183], v184 offset:2048
	ds_read_b128 v[184:187], v184 offset:3072
	s_addc_u32 s31, s17, s29
	s_add_u32 s30, s30, 0x100
	s_addc_u32 s31, s31, 0
	s_add_u32 s61, s50, s28
	s_addc_u32 s64, s51, s29
	s_cmpk_eq_i32 s28, 0x700
	s_cselect_b32 s35, s23, s31
	s_cselect_b32 s34, s58, s30
	s_cselect_b32 s31, s21, s64
	s_cselect_b32 s30, s59, s61
	v_lshl_add_u64 v[188:189], v[148:149], 0, s[28:29]
	s_add_i32 m0, s13, 0xc000
	ds_read_b128 v[192:195], v154
	ds_read_b128 v[196:199], v154 offset:1024
	ds_read_b128 v[200:203], v154 offset:2048
	ds_read_b128 v[204:207], v154 offset:3072
	ds_read_b128 v[208:211], v154 offset:4096
	ds_read_b128 v[218:221], v154 offset:5120
	ds_read_b128 v[226:229], v154 offset:6144
	ds_read_b128 v[230:233], v154 offset:7168
	global_load_lds_dwordx4 v[188:189], off
	v_lshl_add_u64 v[188:189], v[150:151], 0, s[28:29]
	s_add_i32 m0, s13, 0xe000
	s_nop 0
	global_load_lds_dwordx4 v[188:189], off
	s_waitcnt vmcnt(8)
	s_waitcnt lgkmcnt(0)
	v_mfma_f32_16x16x32_bf16 v[128:131], v[156:159], v[192:195], v[128:131]
	v_mfma_f32_16x16x32_bf16 v[124:127], v[164:167], v[192:195], v[124:127]
	v_mfma_f32_16x16x32_bf16 v[112:115], v[156:159], v[200:203], v[112:115]
	v_mfma_f32_16x16x32_bf16 v[108:111], v[164:167], v[200:203], v[108:111]
	v_mfma_f32_16x16x32_bf16 v[96:99], v[156:159], v[208:211], v[96:99]
	v_mfma_f32_16x16x32_bf16 v[92:95], v[164:167], v[208:211], v[92:95]
	v_mfma_f32_16x16x32_bf16 v[80:83], v[156:159], v[226:229], v[80:83]
	v_mfma_f32_16x16x32_bf16 v[76:79], v[164:167], v[226:229], v[76:79]
	v_mfma_f32_16x16x32_bf16 v[128:131], v[160:163], v[196:199], v[128:131]
	v_mfma_f32_16x16x32_bf16 v[124:127], v[168:171], v[196:199], v[124:127]
	v_mfma_f32_16x16x32_bf16 v[112:115], v[160:163], v[204:207], v[112:115]
	v_mfma_f32_16x16x32_bf16 v[108:111], v[168:171], v[204:207], v[108:111]
	v_mfma_f32_16x16x32_bf16 v[96:99], v[160:163], v[218:221], v[96:99]
	v_mfma_f32_16x16x32_bf16 v[92:95], v[168:171], v[218:221], v[92:95]
	v_mfma_f32_16x16x32_bf16 v[80:83], v[160:163], v[230:233], v[80:83]
	v_mfma_f32_16x16x32_bf16 v[76:79], v[168:171], v[230:233], v[76:79]
	s_barrier
	s_setprio 1
	s_waitcnt lgkmcnt(0)
	v_mfma_f32_16x16x32_bf16 v[120:123], v[172:175], v[192:195], v[120:123]
	v_mfma_f32_16x16x32_bf16 v[116:119], v[180:183], v[192:195], v[116:119]
	v_mfma_f32_16x16x32_bf16 v[104:107], v[172:175], v[200:203], v[104:107]
	v_mfma_f32_16x16x32_bf16 v[100:103], v[180:183], v[200:203], v[100:103]
	v_mfma_f32_16x16x32_bf16 v[88:91], v[172:175], v[208:211], v[88:91]
	v_mfma_f32_16x16x32_bf16 v[84:87], v[180:183], v[208:211], v[84:87]
	v_mfma_f32_16x16x32_bf16 v[72:75], v[172:175], v[226:229], v[72:75]
	v_mfma_f32_16x16x32_bf16 v[68:71], v[180:183], v[226:229], v[68:71]
	v_mfma_f32_16x16x32_bf16 v[120:123], v[176:179], v[196:199], v[120:123]
	v_mfma_f32_16x16x32_bf16 v[116:119], v[184:187], v[196:199], v[116:119]
	v_mfma_f32_16x16x32_bf16 v[104:107], v[176:179], v[204:207], v[104:107]
	v_mfma_f32_16x16x32_bf16 v[100:103], v[184:187], v[204:207], v[100:103]
	v_mfma_f32_16x16x32_bf16 v[88:91], v[176:179], v[218:221], v[88:91]
	v_mfma_f32_16x16x32_bf16 v[84:87], v[184:187], v[218:221], v[84:87]
	v_mfma_f32_16x16x32_bf16 v[72:75], v[176:179], v[230:233], v[72:75]
	v_mfma_f32_16x16x32_bf16 v[68:71], v[184:187], v[230:233], v[68:71]
	s_setprio 0
	s_barrier
	s_add_i32 s61, s47, s40
	v_lshl_add_u64 v[188:189], s[30:31], 0, v[134:135]
	s_mov_b32 m0, s61
	ds_read_b128 v[192:195], v154 offset:16384
	ds_read_b128 v[196:199], v154 offset:17408
	ds_read_b128 v[200:203], v154 offset:18432
	ds_read_b128 v[204:207], v154 offset:19456
	ds_read_b128 v[208:211], v154 offset:20480
	ds_read_b128 v[218:221], v154 offset:21504
	ds_read_b128 v[226:229], v154 offset:22528
	ds_read_b128 v[230:233], v154 offset:23552
	global_load_lds_dwordx4 v[188:189], off
	s_add_i32 m0, s61, 0x2000
	s_add_u32 s64, s30, 0x40000
	v_lshl_add_u64 v[234:235], s[30:31], 0, v[138:139]
	s_addc_u32 s65, s31, 0
	s_add_i32 s61, s48, s40
	global_load_lds_dwordx4 v[234:235], off
	v_lshl_add_u64 v[236:237], s[64:65], 0, v[134:135]
	s_mov_b32 m0, s61
	v_lshl_add_u64 v[238:239], s[34:35], 0, v[136:137]
	global_load_lds_dwordx4 v[236:237], off
	v_lshl_add_u64 v[236:237], s[64:65], 0, v[138:139]
	s_add_i32 m0, s61, 0x2000
	s_nop 0
	global_load_lds_dwordx4 v[236:237], off
	v_lshl_add_u64 v[236:237], s[34:35], 0, v[132:133]
	s_mov_b32 m0, s13
	s_nop 0
	global_load_lds_dwordx4 v[236:237], off
	s_mov_b32 m0, s41
	s_nop 0
	global_load_lds_dwordx4 v[238:239], off
	s_waitcnt vmcnt(8)
	s_waitcnt lgkmcnt(0)
	v_mfma_f32_16x16x32_bf16 v[64:67], v[156:159], v[192:195], v[64:67]
	v_mfma_f32_16x16x32_bf16 v[60:63], v[164:167], v[192:195], v[60:63]
	v_mfma_f32_16x16x32_bf16 v[48:51], v[156:159], v[200:203], v[48:51]
	v_mfma_f32_16x16x32_bf16 v[44:47], v[164:167], v[200:203], v[44:47]
	v_mfma_f32_16x16x32_bf16 v[32:35], v[156:159], v[208:211], v[32:35]
	v_mfma_f32_16x16x32_bf16 v[28:31], v[164:167], v[208:211], v[28:31]
	v_mfma_f32_16x16x32_bf16 v[16:19], v[156:159], v[226:229], v[16:19]
	v_mfma_f32_16x16x32_bf16 v[12:15], v[164:167], v[226:229], v[12:15]
	v_mfma_f32_16x16x32_bf16 v[64:67], v[160:163], v[196:199], v[64:67]
	v_mfma_f32_16x16x32_bf16 v[60:63], v[168:171], v[196:199], v[60:63]
	v_mfma_f32_16x16x32_bf16 v[48:51], v[160:163], v[204:207], v[48:51]
	v_mfma_f32_16x16x32_bf16 v[44:47], v[168:171], v[204:207], v[44:47]
	v_mfma_f32_16x16x32_bf16 v[32:35], v[160:163], v[218:221], v[32:35]
	v_mfma_f32_16x16x32_bf16 v[28:31], v[168:171], v[218:221], v[28:31]
	v_mfma_f32_16x16x32_bf16 v[16:19], v[160:163], v[230:233], v[16:19]
	v_mfma_f32_16x16x32_bf16 v[12:15], v[168:171], v[230:233], v[12:15]
	s_barrier
	s_setprio 1
	s_waitcnt lgkmcnt(0)
	v_mfma_f32_16x16x32_bf16 v[56:59], v[172:175], v[192:195], v[56:59]
	v_mfma_f32_16x16x32_bf16 v[52:55], v[180:183], v[192:195], v[52:55]
	v_mfma_f32_16x16x32_bf16 v[40:43], v[172:175], v[200:203], v[40:43]
	v_mfma_f32_16x16x32_bf16 v[36:39], v[180:183], v[200:203], v[36:39]
	v_mfma_f32_16x16x32_bf16 v[24:27], v[172:175], v[208:211], v[24:27]
	v_mfma_f32_16x16x32_bf16 v[20:23], v[180:183], v[208:211], v[20:23]
	v_mfma_f32_16x16x32_bf16 v[8:11], v[172:175], v[226:229], v[8:11]
	v_mfma_f32_16x16x32_bf16 v[4:7], v[180:183], v[226:229], v[4:7]
	v_mfma_f32_16x16x32_bf16 v[56:59], v[176:179], v[196:199], v[56:59]
	v_mfma_f32_16x16x32_bf16 v[52:55], v[184:187], v[196:199], v[52:55]
	v_mfma_f32_16x16x32_bf16 v[40:43], v[176:179], v[204:207], v[40:43]
	v_mfma_f32_16x16x32_bf16 v[36:39], v[184:187], v[204:207], v[36:39]
	v_mfma_f32_16x16x32_bf16 v[24:27], v[176:179], v[218:221], v[24:27]
	v_mfma_f32_16x16x32_bf16 v[20:23], v[184:187], v[218:221], v[20:23]
	v_mfma_f32_16x16x32_bf16 v[8:11], v[176:179], v[230:233], v[8:11]
	v_mfma_f32_16x16x32_bf16 v[4:7], v[184:187], v[230:233], v[4:7]
	s_setprio 0
	s_barrier
	s_add_i32 s61, 0, 0x18000
	s_add_i32 s64, 0, 0x1c000
	v_add_u32_e32 v168, s61, v153
	v_add_u32_e32 v184, s64, v153
	ds_read_b128 v[156:159], v168
	ds_read_b128 v[160:163], v168 offset:1024
	ds_read_b128 v[164:167], v168 offset:2048
	ds_read_b128 v[168:171], v168 offset:3072
	ds_read_b128 v[172:175], v184
	ds_read_b128 v[176:179], v184 offset:1024
	ds_read_b128 v[180:183], v184 offset:2048
	ds_read_b128 v[184:187], v184 offset:3072
	s_add_u32 s34, s34, 0x40000
	s_addc_u32 s35, s35, 0
	s_mov_b32 m0, s42
	v_lshl_add_u64 v[240:241], s[34:35], 0, v[132:133]
	ds_read_b128 v[192:195], v154 offset:32768
	ds_read_b128 v[196:199], v154 offset:33792
	ds_read_b128 v[200:203], v154 offset:34816
	ds_read_b128 v[204:207], v154 offset:35840
	ds_read_b128 v[208:211], v154 offset:36864
	ds_read_b128 v[218:221], v154 offset:37888
	ds_read_b128 v[226:229], v154 offset:38912
	ds_read_b128 v[230:233], v154 offset:39936
	global_load_lds_dwordx4 v[240:241], off
	v_lshl_add_u64 v[240:241], s[34:35], 0, v[136:137]
	s_mov_b32 m0, s43
	s_nop 0
	global_load_lds_dwordx4 v[240:241], off
	s_waitcnt vmcnt(8)
	s_waitcnt lgkmcnt(0)
	v_mfma_f32_16x16x32_bf16 v[128:131], v[156:159], v[192:195], v[128:131]
	v_mfma_f32_16x16x32_bf16 v[124:127], v[164:167], v[192:195], v[124:127]
	v_mfma_f32_16x16x32_bf16 v[112:115], v[156:159], v[200:203], v[112:115]
	v_mfma_f32_16x16x32_bf16 v[108:111], v[164:167], v[200:203], v[108:111]
	v_mfma_f32_16x16x32_bf16 v[96:99], v[156:159], v[208:211], v[96:99]
	v_mfma_f32_16x16x32_bf16 v[92:95], v[164:167], v[208:211], v[92:95]
	v_mfma_f32_16x16x32_bf16 v[80:83], v[156:159], v[226:229], v[80:83]
	v_mfma_f32_16x16x32_bf16 v[76:79], v[164:167], v[226:229], v[76:79]
	v_mfma_f32_16x16x32_bf16 v[128:131], v[160:163], v[196:199], v[128:131]
	v_mfma_f32_16x16x32_bf16 v[124:127], v[168:171], v[196:199], v[124:127]
	v_mfma_f32_16x16x32_bf16 v[112:115], v[160:163], v[204:207], v[112:115]
	v_mfma_f32_16x16x32_bf16 v[108:111], v[168:171], v[204:207], v[108:111]
	v_mfma_f32_16x16x32_bf16 v[96:99], v[160:163], v[218:221], v[96:99]
	v_mfma_f32_16x16x32_bf16 v[92:95], v[168:171], v[218:221], v[92:95]
	v_mfma_f32_16x16x32_bf16 v[80:83], v[160:163], v[230:233], v[80:83]
	v_mfma_f32_16x16x32_bf16 v[76:79], v[168:171], v[230:233], v[76:79]
	s_barrier
	s_setprio 1
	s_waitcnt lgkmcnt(0)
	v_mfma_f32_16x16x32_bf16 v[120:123], v[172:175], v[192:195], v[120:123]
	v_mfma_f32_16x16x32_bf16 v[116:119], v[180:183], v[192:195], v[116:119]
	v_mfma_f32_16x16x32_bf16 v[104:107], v[172:175], v[200:203], v[104:107]
	v_mfma_f32_16x16x32_bf16 v[100:103], v[180:183], v[200:203], v[100:103]
	v_mfma_f32_16x16x32_bf16 v[88:91], v[172:175], v[208:211], v[88:91]
	v_mfma_f32_16x16x32_bf16 v[84:87], v[180:183], v[208:211], v[84:87]
	v_mfma_f32_16x16x32_bf16 v[72:75], v[172:175], v[226:229], v[72:75]
	v_mfma_f32_16x16x32_bf16 v[68:71], v[180:183], v[226:229], v[68:71]
	v_mfma_f32_16x16x32_bf16 v[120:123], v[176:179], v[196:199], v[120:123]
	v_mfma_f32_16x16x32_bf16 v[116:119], v[184:187], v[196:199], v[116:119]
	v_mfma_f32_16x16x32_bf16 v[104:107], v[176:179], v[204:207], v[104:107]
	v_mfma_f32_16x16x32_bf16 v[100:103], v[184:187], v[204:207], v[100:103]
	v_mfma_f32_16x16x32_bf16 v[88:91], v[176:179], v[218:221], v[88:91]
	v_mfma_f32_16x16x32_bf16 v[84:87], v[184:187], v[218:221], v[84:87]
	v_mfma_f32_16x16x32_bf16 v[72:75], v[176:179], v[230:233], v[72:75]
	v_mfma_f32_16x16x32_bf16 v[68:71], v[184:187], v[230:233], v[68:71]
	s_setprio 0
	s_barrier
	s_add_i32 s34, s61, s40
	v_lshl_add_u64 v[188:189], v[188:189], 0, s[18:19]
	s_mov_b32 m0, s34
	ds_read_b128 v[192:195], v154 offset:49152
	ds_read_b128 v[196:199], v154 offset:50176
	ds_read_b128 v[200:203], v154 offset:51200
	ds_read_b128 v[204:207], v154 offset:52224
	ds_read_b128 v[208:211], v154 offset:53248
	ds_read_b128 v[218:221], v154 offset:54272
	ds_read_b128 v[226:229], v154 offset:55296
	ds_read_b128 v[230:233], v154 offset:56320
	global_load_lds_dwordx4 v[188:189], off
	s_add_i32 m0, s34, 0x2000
	s_add_u32 s30, s30, 0x40080
	v_lshl_add_u64 v[188:189], v[234:235], 0, s[18:19]
	s_addc_u32 s31, s31, 0
	s_add_i32 s34, s64, s40
	global_load_lds_dwordx4 v[188:189], off
	v_lshl_add_u64 v[188:189], s[30:31], 0, v[134:135]
	s_mov_b32 m0, s34
	s_nop 0
	global_load_lds_dwordx4 v[188:189], off
	v_lshl_add_u64 v[188:189], s[30:31], 0, v[138:139]
	s_add_i32 m0, s34, 0x2000
	s_nop 0
	global_load_lds_dwordx4 v[188:189], off
	v_lshl_add_u64 v[188:189], v[236:237], 0, s[18:19]
	s_mov_b32 m0, s44
	s_nop 0
	global_load_lds_dwordx4 v[188:189], off
	v_lshl_add_u64 v[188:189], v[238:239], 0, s[18:19]
	s_mov_b32 m0, s45
	s_nop 0
	global_load_lds_dwordx4 v[188:189], off
	s_waitcnt vmcnt(8)
	s_waitcnt lgkmcnt(0)
	v_mfma_f32_16x16x32_bf16 v[64:67], v[156:159], v[192:195], v[64:67]
	v_mfma_f32_16x16x32_bf16 v[60:63], v[164:167], v[192:195], v[60:63]
	v_mfma_f32_16x16x32_bf16 v[48:51], v[156:159], v[200:203], v[48:51]
	v_mfma_f32_16x16x32_bf16 v[44:47], v[164:167], v[200:203], v[44:47]
	v_mfma_f32_16x16x32_bf16 v[32:35], v[156:159], v[208:211], v[32:35]
	v_mfma_f32_16x16x32_bf16 v[28:31], v[164:167], v[208:211], v[28:31]
	v_mfma_f32_16x16x32_bf16 v[16:19], v[156:159], v[226:229], v[16:19]
	v_mfma_f32_16x16x32_bf16 v[12:15], v[164:167], v[226:229], v[12:15]
	v_mfma_f32_16x16x32_bf16 v[64:67], v[160:163], v[196:199], v[64:67]
	v_mfma_f32_16x16x32_bf16 v[60:63], v[168:171], v[196:199], v[60:63]
	v_mfma_f32_16x16x32_bf16 v[48:51], v[160:163], v[204:207], v[48:51]
	v_mfma_f32_16x16x32_bf16 v[44:47], v[168:171], v[204:207], v[44:47]
	v_mfma_f32_16x16x32_bf16 v[32:35], v[160:163], v[218:221], v[32:35]
	v_mfma_f32_16x16x32_bf16 v[28:31], v[168:171], v[218:221], v[28:31]
	v_mfma_f32_16x16x32_bf16 v[16:19], v[160:163], v[230:233], v[16:19]
	v_mfma_f32_16x16x32_bf16 v[12:15], v[168:171], v[230:233], v[12:15]
	s_barrier
	s_setprio 1
	s_waitcnt lgkmcnt(0)
	v_mfma_f32_16x16x32_bf16 v[56:59], v[172:175], v[192:195], v[56:59]
	v_mfma_f32_16x16x32_bf16 v[52:55], v[180:183], v[192:195], v[52:55]
	v_mfma_f32_16x16x32_bf16 v[40:43], v[172:175], v[200:203], v[40:43]
	v_mfma_f32_16x16x32_bf16 v[36:39], v[180:183], v[200:203], v[36:39]
	v_mfma_f32_16x16x32_bf16 v[24:27], v[172:175], v[208:211], v[24:27]
	v_mfma_f32_16x16x32_bf16 v[20:23], v[180:183], v[208:211], v[20:23]
	v_mfma_f32_16x16x32_bf16 v[8:11], v[172:175], v[226:229], v[8:11]
	v_mfma_f32_16x16x32_bf16 v[4:7], v[180:183], v[226:229], v[4:7]
	v_mfma_f32_16x16x32_bf16 v[56:59], v[176:179], v[196:199], v[56:59]
	v_mfma_f32_16x16x32_bf16 v[52:55], v[184:187], v[196:199], v[52:55]
	v_mfma_f32_16x16x32_bf16 v[40:43], v[176:179], v[204:207], v[40:43]
	v_mfma_f32_16x16x32_bf16 v[36:39], v[184:187], v[204:207], v[36:39]
	v_mfma_f32_16x16x32_bf16 v[24:27], v[176:179], v[218:221], v[24:27]
	v_mfma_f32_16x16x32_bf16 v[20:23], v[184:187], v[218:221], v[20:23]
	v_mfma_f32_16x16x32_bf16 v[8:11], v[176:179], v[230:233], v[8:11]
	v_mfma_f32_16x16x32_bf16 v[4:7], v[184:187], v[230:233], v[4:7]
	s_setprio 0
	s_barrier
	s_add_i32 s60, s60, 2
	s_add_u32 s28, s28, 0x100
	s_addc_u32 s29, s29, 0
	s_cmp_gt_u32 s60, 13
	s_cbranch_scc0 .LBB0_679
	s_add_u32 s28, s50, 0xffffff00
	s_addc_u32 s29, s51, -1
	s_andn2_b64 vcc, exec, s[4:5]
	s_cbranch_vccnz .LBB0_670
	v_mov_b32_e32 v4, 0
	s_mov_b32 s6, s20
	s_mov_b32 s12, s22
	s_mov_b64 s[16:17], s[26:27]
	s_mov_b32 s46, s49
	v_mov_b32_e32 v5, v4
	v_mov_b32_e32 v6, v4
	v_mov_b32_e32 v7, v4
	v_mov_b32_e32 v8, v4
	v_mov_b32_e32 v9, v4
	v_mov_b32_e32 v10, v4
	v_mov_b32_e32 v11, v4
	v_mov_b32_e32 v20, v4
	v_mov_b32_e32 v21, v4
	v_mov_b32_e32 v22, v4
	v_mov_b32_e32 v23, v4
	v_mov_b32_e32 v24, v4
	v_mov_b32_e32 v25, v4
	v_mov_b32_e32 v26, v4
	v_mov_b32_e32 v27, v4
	v_mov_b32_e32 v36, v4
	v_mov_b32_e32 v37, v4
	v_mov_b32_e32 v38, v4
	v_mov_b32_e32 v39, v4
	v_mov_b32_e32 v40, v4
	v_mov_b32_e32 v41, v4
	v_mov_b32_e32 v42, v4
	v_mov_b32_e32 v43, v4
	v_mov_b32_e32 v52, v4
	v_mov_b32_e32 v53, v4
	v_mov_b32_e32 v54, v4
	v_mov_b32_e32 v55, v4
	v_mov_b32_e32 v56, v4
	v_mov_b32_e32 v57, v4
	v_mov_b32_e32 v58, v4
	v_mov_b32_e32 v59, v4
	v_mov_b32_e32 v12, v4
	v_mov_b32_e32 v13, v4
	v_mov_b32_e32 v14, v4
	v_mov_b32_e32 v15, v4
	v_mov_b32_e32 v16, v4
	v_mov_b32_e32 v17, v4
	v_mov_b32_e32 v18, v4
	v_mov_b32_e32 v19, v4
	v_mov_b32_e32 v28, v4
	v_mov_b32_e32 v29, v4
	v_mov_b32_e32 v30, v4
	v_mov_b32_e32 v31, v4
	v_mov_b32_e32 v32, v4
	v_mov_b32_e32 v33, v4
	v_mov_b32_e32 v34, v4
	v_mov_b32_e32 v35, v4
	v_mov_b32_e32 v44, v4
	v_mov_b32_e32 v45, v4
	v_mov_b32_e32 v46, v4
	v_mov_b32_e32 v47, v4
	v_mov_b32_e32 v48, v4
	v_mov_b32_e32 v49, v4
	v_mov_b32_e32 v50, v4
	v_mov_b32_e32 v51, v4
	v_mov_b32_e32 v60, v4
	v_mov_b32_e32 v61, v4
	v_mov_b32_e32 v62, v4
	v_mov_b32_e32 v63, v4
	v_mov_b32_e32 v64, v4
	v_mov_b32_e32 v65, v4
	v_mov_b32_e32 v66, v4
	v_mov_b32_e32 v67, v4
	v_mov_b32_e32 v68, v4
	v_mov_b32_e32 v69, v4
	v_mov_b32_e32 v70, v4
	v_mov_b32_e32 v71, v4
	v_mov_b32_e32 v72, v4
	v_mov_b32_e32 v73, v4
	v_mov_b32_e32 v74, v4
	v_mov_b32_e32 v75, v4
	v_mov_b32_e32 v84, v4
	v_mov_b32_e32 v85, v4
	v_mov_b32_e32 v86, v4
	v_mov_b32_e32 v87, v4
	v_mov_b32_e32 v88, v4
	v_mov_b32_e32 v89, v4
	v_mov_b32_e32 v90, v4
	v_mov_b32_e32 v91, v4
	v_mov_b32_e32 v100, v4
	v_mov_b32_e32 v101, v4
	v_mov_b32_e32 v102, v4
	v_mov_b32_e32 v103, v4
	v_mov_b32_e32 v104, v4
	v_mov_b32_e32 v105, v4
	v_mov_b32_e32 v106, v4
	v_mov_b32_e32 v107, v4
	v_mov_b32_e32 v116, v4
	v_mov_b32_e32 v117, v4
	v_mov_b32_e32 v118, v4
	v_mov_b32_e32 v119, v4
	v_mov_b32_e32 v120, v4
	v_mov_b32_e32 v121, v4
	v_mov_b32_e32 v122, v4
	v_mov_b32_e32 v123, v4
	v_mov_b32_e32 v76, v4
	v_mov_b32_e32 v77, v4
	v_mov_b32_e32 v78, v4
	v_mov_b32_e32 v79, v4
	v_mov_b32_e32 v80, v4
	v_mov_b32_e32 v81, v4
	v_mov_b32_e32 v82, v4
	v_mov_b32_e32 v83, v4
	v_mov_b32_e32 v92, v4
	v_mov_b32_e32 v93, v4
	v_mov_b32_e32 v94, v4
	v_mov_b32_e32 v95, v4
	v_mov_b32_e32 v96, v4
	v_mov_b32_e32 v97, v4
	v_mov_b32_e32 v98, v4
	v_mov_b32_e32 v99, v4
	v_mov_b32_e32 v108, v4
	v_mov_b32_e32 v109, v4
	v_mov_b32_e32 v110, v4
	v_mov_b32_e32 v111, v4
	v_mov_b32_e32 v112, v4
	v_mov_b32_e32 v113, v4
	v_mov_b32_e32 v114, v4
	v_mov_b32_e32 v115, v4
	v_mov_b32_e32 v124, v4
	v_mov_b32_e32 v125, v4
	v_mov_b32_e32 v126, v4
	v_mov_b32_e32 v127, v4
	v_mov_b32_e32 v128, v4
	v_mov_b32_e32 v129, v4
	v_mov_b32_e32 v130, v4
	v_mov_b32_e32 v131, v4
	s_andn2_b64 vcc, exec, s[0:1]
	s_cbranch_vccnz .LBB0_671

.LBB0_820:
	ds_read_b128 v[148:151], v158
	ds_read_b128 v[162:165], v158 offset:1024
	ds_read_b128 v[166:169], v158 offset:2048
	ds_read_b128 v[170:173], v158 offset:3072
	ds_read_b128 v[174:177], v159
	ds_read_b128 v[178:181], v159 offset:1024
	ds_read_b128 v[182:185], v159 offset:2048
	ds_read_b128 v[186:189], v159 offset:3072
	s_add_u32 s40, s38, 0xfffc0080
	s_addc_u32 s41, s39, -1
	s_cmp_eq_u32 s71, 12
	s_cselect_b32 s43, s29, s41
	s_cselect_b32 s42, s67, s40
	s_cselect_b32 s41, s27, s70
	s_cselect_b32 s40, s68, s69
	v_lshl_add_u64 v[152:153], s[38:39], 0, v[140:141]
	s_add_i32 m0, s37, 0xc000
	ds_read_b128 v[190:193], v160
	ds_read_b128 v[194:197], v160 offset:1024
	ds_read_b128 v[198:201], v160 offset:2048
	ds_read_b128 v[202:205], v160 offset:3072
	ds_read_b128 v[206:209], v160 offset:4096
	ds_read_b128 v[218:221], v160 offset:5120
	ds_read_b128 v[226:229], v160 offset:6144
	ds_read_b128 v[230:233], v160 offset:7168
	global_load_lds_dwordx4 v[152:153], off
	v_lshl_add_u64 v[152:153], s[38:39], 0, v[142:143]
	s_add_i32 m0, s37, 0xe000
	s_nop 0
	global_load_lds_dwordx4 v[152:153], off
	s_waitcnt vmcnt(8)
	s_waitcnt lgkmcnt(0)
	v_mfma_f32_16x16x32_bf16 v[128:131], v[148:151], v[190:193], v[128:131]
	v_mfma_f32_16x16x32_bf16 v[124:127], v[166:169], v[190:193], v[124:127]
	v_mfma_f32_16x16x32_bf16 v[112:115], v[148:151], v[198:201], v[112:115]
	v_mfma_f32_16x16x32_bf16 v[108:111], v[166:169], v[198:201], v[108:111]
	v_mfma_f32_16x16x32_bf16 v[96:99], v[148:151], v[206:209], v[96:99]
	v_mfma_f32_16x16x32_bf16 v[92:95], v[166:169], v[206:209], v[92:95]
	v_mfma_f32_16x16x32_bf16 v[80:83], v[148:151], v[226:229], v[80:83]
	v_mfma_f32_16x16x32_bf16 v[76:79], v[166:169], v[226:229], v[76:79]
	v_mfma_f32_16x16x32_bf16 v[128:131], v[162:165], v[194:197], v[128:131]
	v_mfma_f32_16x16x32_bf16 v[124:127], v[170:173], v[194:197], v[124:127]
	v_mfma_f32_16x16x32_bf16 v[112:115], v[162:165], v[202:205], v[112:115]
	v_mfma_f32_16x16x32_bf16 v[108:111], v[170:173], v[202:205], v[108:111]
	v_mfma_f32_16x16x32_bf16 v[96:99], v[162:165], v[218:221], v[96:99]
	v_mfma_f32_16x16x32_bf16 v[92:95], v[170:173], v[218:221], v[92:95]
	v_mfma_f32_16x16x32_bf16 v[80:83], v[162:165], v[230:233], v[80:83]
	v_mfma_f32_16x16x32_bf16 v[76:79], v[170:173], v[230:233], v[76:79]
	s_barrier
	s_setprio 1
	s_waitcnt lgkmcnt(0)
	v_mfma_f32_16x16x32_bf16 v[120:123], v[174:177], v[190:193], v[120:123]
	v_mfma_f32_16x16x32_bf16 v[116:119], v[182:185], v[190:193], v[116:119]
	v_mfma_f32_16x16x32_bf16 v[104:107], v[174:177], v[198:201], v[104:107]
	v_mfma_f32_16x16x32_bf16 v[100:103], v[182:185], v[198:201], v[100:103]
	v_mfma_f32_16x16x32_bf16 v[88:91], v[174:177], v[206:209], v[88:91]
	v_mfma_f32_16x16x32_bf16 v[84:87], v[182:185], v[206:209], v[84:87]
	v_mfma_f32_16x16x32_bf16 v[72:75], v[174:177], v[226:229], v[72:75]
	v_mfma_f32_16x16x32_bf16 v[68:71], v[182:185], v[226:229], v[68:71]
	v_mfma_f32_16x16x32_bf16 v[120:123], v[178:181], v[194:197], v[120:123]
	v_mfma_f32_16x16x32_bf16 v[116:119], v[186:189], v[194:197], v[116:119]
	v_mfma_f32_16x16x32_bf16 v[104:107], v[178:181], v[202:205], v[104:107]
	v_mfma_f32_16x16x32_bf16 v[100:103], v[186:189], v[202:205], v[100:103]
	v_mfma_f32_16x16x32_bf16 v[88:91], v[178:181], v[218:221], v[88:91]
	v_mfma_f32_16x16x32_bf16 v[84:87], v[186:189], v[218:221], v[84:87]
	v_mfma_f32_16x16x32_bf16 v[72:75], v[178:181], v[230:233], v[72:75]
	v_mfma_f32_16x16x32_bf16 v[68:71], v[186:189], v[230:233], v[68:71]
	s_setprio 0
	s_barrier
	s_add_i32 s72, s58, s33
	v_lshl_add_u64 v[152:153], s[40:41], 0, v[134:135]
	s_mov_b32 m0, s72
	ds_read_b128 v[190:193], v160 offset:16384
	ds_read_b128 v[194:197], v160 offset:17408
	ds_read_b128 v[198:201], v160 offset:18432
	ds_read_b128 v[202:205], v160 offset:19456
	ds_read_b128 v[206:209], v160 offset:20480
	ds_read_b128 v[218:221], v160 offset:21504
	ds_read_b128 v[226:229], v160 offset:22528
	ds_read_b128 v[230:233], v160 offset:23552
	global_load_lds_dwordx4 v[152:153], off
	s_add_i32 m0, s72, 0x2000
	s_add_u32 s72, s40, 0x40000
	v_lshl_add_u64 v[210:211], s[40:41], 0, v[138:139]
	s_addc_u32 s73, s41, 0
	s_add_i32 s74, s59, s33
	global_load_lds_dwordx4 v[210:211], off
	v_lshl_add_u64 v[234:235], s[72:73], 0, v[134:135]
	s_mov_b32 m0, s74
	v_lshl_add_u64 v[236:237], s[42:43], 0, v[136:137]
	global_load_lds_dwordx4 v[234:235], off
	v_lshl_add_u64 v[234:235], s[72:73], 0, v[138:139]
	s_add_i32 m0, s74, 0x2000
	s_nop 0
	global_load_lds_dwordx4 v[234:235], off
	v_lshl_add_u64 v[234:235], s[42:43], 0, v[132:133]
	s_mov_b32 m0, s37
	s_nop 0
	global_load_lds_dwordx4 v[234:235], off
	s_mov_b32 m0, s44
	s_nop 0
	global_load_lds_dwordx4 v[236:237], off
	s_waitcnt vmcnt(8)
	s_waitcnt lgkmcnt(0)
	v_mfma_f32_16x16x32_bf16 v[64:67], v[148:151], v[190:193], v[64:67]
	v_mfma_f32_16x16x32_bf16 v[60:63], v[166:169], v[190:193], v[60:63]
	v_mfma_f32_16x16x32_bf16 v[48:51], v[148:151], v[198:201], v[48:51]
	v_mfma_f32_16x16x32_bf16 v[44:47], v[166:169], v[198:201], v[44:47]
	v_mfma_f32_16x16x32_bf16 v[32:35], v[148:151], v[206:209], v[32:35]
	v_mfma_f32_16x16x32_bf16 v[28:31], v[166:169], v[206:209], v[28:31]
	v_mfma_f32_16x16x32_bf16 v[16:19], v[148:151], v[226:229], v[16:19]
	v_mfma_f32_16x16x32_bf16 v[12:15], v[166:169], v[226:229], v[12:15]
	v_mfma_f32_16x16x32_bf16 v[64:67], v[162:165], v[194:197], v[64:67]
	v_mfma_f32_16x16x32_bf16 v[60:63], v[170:173], v[194:197], v[60:63]
	v_mfma_f32_16x16x32_bf16 v[48:51], v[162:165], v[202:205], v[48:51]
	v_mfma_f32_16x16x32_bf16 v[44:47], v[170:173], v[202:205], v[44:47]
	v_mfma_f32_16x16x32_bf16 v[32:35], v[162:165], v[218:221], v[32:35]
	v_mfma_f32_16x16x32_bf16 v[28:31], v[170:173], v[218:221], v[28:31]
	v_mfma_f32_16x16x32_bf16 v[16:19], v[162:165], v[230:233], v[16:19]
	v_mfma_f32_16x16x32_bf16 v[12:15], v[170:173], v[230:233], v[12:15]
	s_barrier
	s_setprio 1
	s_waitcnt lgkmcnt(0)
	v_mfma_f32_16x16x32_bf16 v[56:59], v[174:177], v[190:193], v[56:59]
	v_mfma_f32_16x16x32_bf16 v[52:55], v[182:185], v[190:193], v[52:55]
	v_mfma_f32_16x16x32_bf16 v[40:43], v[174:177], v[198:201], v[40:43]
	v_mfma_f32_16x16x32_bf16 v[36:39], v[182:185], v[198:201], v[36:39]
	v_mfma_f32_16x16x32_bf16 v[24:27], v[174:177], v[206:209], v[24:27]
	v_mfma_f32_16x16x32_bf16 v[20:23], v[182:185], v[206:209], v[20:23]
	v_mfma_f32_16x16x32_bf16 v[8:11], v[174:177], v[226:229], v[8:11]
	v_mfma_f32_16x16x32_bf16 v[4:7], v[182:185], v[226:229], v[4:7]
	v_mfma_f32_16x16x32_bf16 v[56:59], v[178:181], v[194:197], v[56:59]
	v_mfma_f32_16x16x32_bf16 v[52:55], v[186:189], v[194:197], v[52:55]
	v_mfma_f32_16x16x32_bf16 v[40:43], v[178:181], v[202:205], v[40:43]
	v_mfma_f32_16x16x32_bf16 v[36:39], v[186:189], v[202:205], v[36:39]
	v_mfma_f32_16x16x32_bf16 v[24:27], v[178:181], v[218:221], v[24:27]
	v_mfma_f32_16x16x32_bf16 v[20:23], v[186:189], v[218:221], v[20:23]
	v_mfma_f32_16x16x32_bf16 v[8:11], v[178:181], v[230:233], v[8:11]
	v_mfma_f32_16x16x32_bf16 v[4:7], v[186:189], v[230:233], v[4:7]
	s_setprio 0
	s_barrier
	s_add_i32 s72, 0, 0x18000
	v_add_u32_e32 v161, s72, v154
	s_add_i32 s73, 0, 0x1c000
	ds_read_b128 v[148:151], v161
	ds_read_b128 v[162:165], v161 offset:1024
	ds_read_b128 v[166:169], v161 offset:2048
	ds_read_b128 v[170:173], v161 offset:3072
	v_add_u32_e32 v161, s73, v154
	ds_read_b128 v[174:177], v161
	ds_read_b128 v[178:181], v161 offset:1024
	ds_read_b128 v[182:185], v161 offset:2048
	ds_read_b128 v[186:189], v161 offset:3072
	s_add_u32 s42, s42, 0x40000
	s_addc_u32 s43, s43, 0
	s_mov_b32 m0, s45
	v_lshl_add_u64 v[238:239], s[42:43], 0, v[132:133]
	ds_read_b128 v[190:193], v160 offset:32768
	ds_read_b128 v[194:197], v160 offset:33792
	ds_read_b128 v[198:201], v160 offset:34816
	ds_read_b128 v[202:205], v160 offset:35840
	ds_read_b128 v[206:209], v160 offset:36864
	ds_read_b128 v[218:221], v160 offset:37888
	ds_read_b128 v[226:229], v160 offset:38912
	ds_read_b128 v[230:233], v160 offset:39936
	global_load_lds_dwordx4 v[238:239], off
	v_lshl_add_u64 v[238:239], s[42:43], 0, v[136:137]
	s_mov_b32 m0, s46
	s_nop 0
	global_load_lds_dwordx4 v[238:239], off
	s_waitcnt vmcnt(8)
	s_waitcnt lgkmcnt(0)
	v_mfma_f32_16x16x32_bf16 v[128:131], v[148:151], v[190:193], v[128:131]
	v_mfma_f32_16x16x32_bf16 v[124:127], v[166:169], v[190:193], v[124:127]
	v_mfma_f32_16x16x32_bf16 v[112:115], v[148:151], v[198:201], v[112:115]
	v_mfma_f32_16x16x32_bf16 v[108:111], v[166:169], v[198:201], v[108:111]
	v_mfma_f32_16x16x32_bf16 v[96:99], v[148:151], v[206:209], v[96:99]
	v_mfma_f32_16x16x32_bf16 v[92:95], v[166:169], v[206:209], v[92:95]
	v_mfma_f32_16x16x32_bf16 v[80:83], v[148:151], v[226:229], v[80:83]
	v_mfma_f32_16x16x32_bf16 v[76:79], v[166:169], v[226:229], v[76:79]
	v_mfma_f32_16x16x32_bf16 v[128:131], v[162:165], v[194:197], v[128:131]
	v_mfma_f32_16x16x32_bf16 v[124:127], v[170:173], v[194:197], v[124:127]
	v_mfma_f32_16x16x32_bf16 v[112:115], v[162:165], v[202:205], v[112:115]
	v_mfma_f32_16x16x32_bf16 v[108:111], v[170:173], v[202:205], v[108:111]
	v_mfma_f32_16x16x32_bf16 v[96:99], v[162:165], v[218:221], v[96:99]
	v_mfma_f32_16x16x32_bf16 v[92:95], v[170:173], v[218:221], v[92:95]
	v_mfma_f32_16x16x32_bf16 v[80:83], v[162:165], v[230:233], v[80:83]
	v_mfma_f32_16x16x32_bf16 v[76:79], v[170:173], v[230:233], v[76:79]
	s_barrier
	s_setprio 1
	s_waitcnt lgkmcnt(0)
	v_mfma_f32_16x16x32_bf16 v[120:123], v[174:177], v[190:193], v[120:123]
	v_mfma_f32_16x16x32_bf16 v[116:119], v[182:185], v[190:193], v[116:119]
	v_mfma_f32_16x16x32_bf16 v[104:107], v[174:177], v[198:201], v[104:107]
	v_mfma_f32_16x16x32_bf16 v[100:103], v[182:185], v[198:201], v[100:103]
	v_mfma_f32_16x16x32_bf16 v[88:91], v[174:177], v[206:209], v[88:91]
	v_mfma_f32_16x16x32_bf16 v[84:87], v[182:185], v[206:209], v[84:87]
	v_mfma_f32_16x16x32_bf16 v[72:75], v[174:177], v[226:229], v[72:75]
	v_mfma_f32_16x16x32_bf16 v[68:71], v[182:185], v[226:229], v[68:71]
	v_mfma_f32_16x16x32_bf16 v[120:123], v[178:181], v[194:197], v[120:123]
	v_mfma_f32_16x16x32_bf16 v[116:119], v[186:189], v[194:197], v[116:119]
	v_mfma_f32_16x16x32_bf16 v[104:107], v[178:181], v[202:205], v[104:107]
	v_mfma_f32_16x16x32_bf16 v[100:103], v[186:189], v[202:205], v[100:103]
	v_mfma_f32_16x16x32_bf16 v[88:91], v[178:181], v[218:221], v[88:91]
	v_mfma_f32_16x16x32_bf16 v[84:87], v[186:189], v[218:221], v[84:87]
	v_mfma_f32_16x16x32_bf16 v[72:75], v[178:181], v[230:233], v[72:75]
	v_mfma_f32_16x16x32_bf16 v[68:71], v[186:189], v[230:233], v[68:71]
	s_setprio 0
	s_barrier
	s_add_i32 s42, s72, s33
	v_lshl_add_u64 v[152:153], v[152:153], 0, s[12:13]
	s_mov_b32 m0, s42
	ds_read_b128 v[190:193], v160 offset:49152
	ds_read_b128 v[194:197], v160 offset:50176
	ds_read_b128 v[198:201], v160 offset:51200
	ds_read_b128 v[202:205], v160 offset:52224
	ds_read_b128 v[206:209], v160 offset:53248
	ds_read_b128 v[218:221], v160 offset:54272
	ds_read_b128 v[226:229], v160 offset:55296
	ds_read_b128 v[230:233], v160 offset:56320
	global_load_lds_dwordx4 v[152:153], off
	s_add_i32 m0, s42, 0x2000
	s_add_u32 s40, s40, 0x40080
	v_lshl_add_u64 v[152:153], v[210:211], 0, s[12:13]
	s_addc_u32 s41, s41, 0
	s_add_i32 s42, s73, s33
	global_load_lds_dwordx4 v[152:153], off
	v_lshl_add_u64 v[152:153], s[40:41], 0, v[134:135]
	s_mov_b32 m0, s42
	s_nop 0
	global_load_lds_dwordx4 v[152:153], off
	v_lshl_add_u64 v[152:153], s[40:41], 0, v[138:139]
	s_add_i32 m0, s42, 0x2000
	s_nop 0
	global_load_lds_dwordx4 v[152:153], off
	v_lshl_add_u64 v[152:153], v[234:235], 0, s[12:13]
	s_mov_b32 m0, s48
	s_nop 0
	global_load_lds_dwordx4 v[152:153], off
	v_lshl_add_u64 v[152:153], v[236:237], 0, s[12:13]
	s_mov_b32 m0, s49
	s_nop 0
	global_load_lds_dwordx4 v[152:153], off
	s_waitcnt vmcnt(8)
	s_waitcnt lgkmcnt(0)
	v_mfma_f32_16x16x32_bf16 v[64:67], v[148:151], v[190:193], v[64:67]
	v_mfma_f32_16x16x32_bf16 v[60:63], v[166:169], v[190:193], v[60:63]
	v_mfma_f32_16x16x32_bf16 v[48:51], v[148:151], v[198:201], v[48:51]
	v_mfma_f32_16x16x32_bf16 v[44:47], v[166:169], v[198:201], v[44:47]
	v_mfma_f32_16x16x32_bf16 v[32:35], v[148:151], v[206:209], v[32:35]
	v_mfma_f32_16x16x32_bf16 v[28:31], v[166:169], v[206:209], v[28:31]
	v_mfma_f32_16x16x32_bf16 v[16:19], v[148:151], v[226:229], v[16:19]
	v_mfma_f32_16x16x32_bf16 v[12:15], v[166:169], v[226:229], v[12:15]
	v_mfma_f32_16x16x32_bf16 v[64:67], v[162:165], v[194:197], v[64:67]
	v_mfma_f32_16x16x32_bf16 v[60:63], v[170:173], v[194:197], v[60:63]
	v_mfma_f32_16x16x32_bf16 v[48:51], v[162:165], v[202:205], v[48:51]
	v_mfma_f32_16x16x32_bf16 v[44:47], v[170:173], v[202:205], v[44:47]
	v_mfma_f32_16x16x32_bf16 v[32:35], v[162:165], v[218:221], v[32:35]
	v_mfma_f32_16x16x32_bf16 v[28:31], v[170:173], v[218:221], v[28:31]
	v_mfma_f32_16x16x32_bf16 v[16:19], v[162:165], v[230:233], v[16:19]
	v_mfma_f32_16x16x32_bf16 v[12:15], v[170:173], v[230:233], v[12:15]
	s_barrier
	s_setprio 1
	s_waitcnt lgkmcnt(0)
	v_mfma_f32_16x16x32_bf16 v[56:59], v[174:177], v[190:193], v[56:59]
	v_mfma_f32_16x16x32_bf16 v[52:55], v[182:185], v[190:193], v[52:55]
	v_mfma_f32_16x16x32_bf16 v[40:43], v[174:177], v[198:201], v[40:43]
	v_mfma_f32_16x16x32_bf16 v[36:39], v[182:185], v[198:201], v[36:39]
	v_mfma_f32_16x16x32_bf16 v[24:27], v[174:177], v[206:209], v[24:27]
	v_mfma_f32_16x16x32_bf16 v[20:23], v[182:185], v[206:209], v[20:23]
	v_mfma_f32_16x16x32_bf16 v[8:11], v[174:177], v[226:229], v[8:11]
	v_mfma_f32_16x16x32_bf16 v[4:7], v[182:185], v[226:229], v[4:7]
	v_mfma_f32_16x16x32_bf16 v[56:59], v[178:181], v[194:197], v[56:59]
	v_mfma_f32_16x16x32_bf16 v[52:55], v[186:189], v[194:197], v[52:55]
	v_mfma_f32_16x16x32_bf16 v[40:43], v[178:181], v[202:205], v[40:43]
	v_mfma_f32_16x16x32_bf16 v[36:39], v[186:189], v[202:205], v[36:39]
	v_mfma_f32_16x16x32_bf16 v[24:27], v[178:181], v[218:221], v[24:27]
	v_mfma_f32_16x16x32_bf16 v[20:23], v[186:189], v[218:221], v[20:23]
	v_mfma_f32_16x16x32_bf16 v[8:11], v[178:181], v[230:233], v[8:11]
	v_mfma_f32_16x16x32_bf16 v[4:7], v[186:189], v[230:233], v[4:7]
	s_setprio 0
	s_barrier
	s_add_i32 s71, s71, 2
	s_add_u32 s38, s38, 0x100
	s_addc_u32 s39, s39, 0
	s_add_u32 s69, s69, 0x100
	s_addc_u32 s70, s70, 0
	s_cmp_gt_u32 s71, 13
	s_cbranch_scc0 .LBB0_820
	s_and_b64 vcc, exec, s[16:17]
	s_cbranch_vccz .LBB0_823
	s_barrier

.LBB0_936:
	v_add_u32_e32 v93, s51, v152
	ds_read_b128 v[154:157], v93
	ds_read_b128 v[158:161], v93 offset:1024
	ds_read_b128 v[166:169], v93 offset:2048
	ds_read_b128 v[170:173], v93 offset:3072
	v_add_u32_e32 v93, s58, v152
	ds_read_b128 v[174:177], v93
	ds_read_b128 v[178:181], v93 offset:1024
	ds_read_b128 v[182:185], v93 offset:2048
	ds_read_b128 v[186:189], v93 offset:3072
	s_add_i32 s67, s34, 2
	s_add_u32 s68, s30, 0x80
	s_addc_u32 s35, s31, 0
	s_cmp_eq_u32 s50, s34
	s_cselect_b32 s34, s6, s68
	s_cselect_b32 s35, s7, s35
	s_cselect_b32 s69, s29, s66
	s_cselect_b32 s68, s28, s65
	v_lshl_add_u64 v[94:95], s[30:31], 0, v[120:121]
	s_add_i32 m0, s42, 0xc000
	ds_read_b128 v[190:193], v153
	ds_read_b128 v[194:197], v153 offset:1024
	ds_read_b128 v[198:201], v153 offset:2048
	ds_read_b128 v[202:205], v153 offset:3072
	ds_read_b128 v[206:209], v153 offset:4096
	ds_read_b128 v[218:221], v153 offset:5120
	ds_read_b128 v[226:229], v153 offset:6144
	ds_read_b128 v[230:233], v153 offset:7168
	global_load_lds_dwordx4 v[94:95], off
	v_lshl_add_u64 v[94:95], s[30:31], 0, v[122:123]
	s_add_i32 m0, s42, 0xe000
	s_nop 0
	global_load_lds_dwordx4 v[94:95], off
	s_waitcnt vmcnt(8)
	s_waitcnt lgkmcnt(0)
	v_mfma_f32_16x16x32_bf16 v[148:151], v[154:157], v[190:193], v[148:151]
	v_mfma_f32_16x16x32_bf16 v[144:147], v[166:169], v[190:193], v[144:147]
	v_mfma_f32_16x16x32_bf16 v[128:131], v[154:157], v[198:201], v[128:131]
	v_mfma_f32_16x16x32_bf16 v[124:127], v[166:169], v[198:201], v[124:127]
	v_mfma_f32_16x16x32_bf16 v[104:107], v[154:157], v[206:209], v[104:107]
	v_mfma_f32_16x16x32_bf16 v[94:97], v[166:169], v[206:209], v[96:99]
	v_mfma_f32_16x16x32_bf16 v[80:83], v[154:157], v[226:229], v[80:83]
	v_mfma_f32_16x16x32_bf16 v[76:79], v[166:169], v[226:229], v[76:79]
	v_mfma_f32_16x16x32_bf16 v[148:151], v[158:161], v[194:197], v[148:151]
	v_mfma_f32_16x16x32_bf16 v[144:147], v[170:173], v[194:197], v[144:147]
	v_mfma_f32_16x16x32_bf16 v[128:131], v[158:161], v[202:205], v[128:131]
	v_mfma_f32_16x16x32_bf16 v[124:127], v[170:173], v[202:205], v[124:127]
	v_mfma_f32_16x16x32_bf16 v[104:107], v[158:161], v[218:221], v[104:107]
	v_mfma_f32_16x16x32_bf16 v[94:97], v[170:173], v[218:221], v[94:97]
	v_mfma_f32_16x16x32_bf16 v[80:83], v[158:161], v[230:233], v[80:83]
	v_mfma_f32_16x16x32_bf16 v[76:79], v[170:173], v[230:233], v[76:79]
	s_barrier
	s_setprio 1
	s_waitcnt lgkmcnt(0)
	v_mfma_f32_16x16x32_bf16 v[140:143], v[174:177], v[190:193], v[140:143]
	v_mfma_f32_16x16x32_bf16 v[136:139], v[182:185], v[190:193], v[136:139]
	v_mfma_f32_16x16x32_bf16 v[116:119], v[174:177], v[198:201], v[116:119]
	v_mfma_f32_16x16x32_bf16 v[108:111], v[182:185], v[198:201], v[108:111]
	v_mfma_f32_16x16x32_bf16 v[88:91], v[174:177], v[206:209], v[88:91]
	v_mfma_f32_16x16x32_bf16 v[84:87], v[182:185], v[206:209], v[84:87]
	v_mfma_f32_16x16x32_bf16 v[72:75], v[174:177], v[226:229], v[72:75]
	v_mfma_f32_16x16x32_bf16 v[68:71], v[182:185], v[226:229], v[68:71]
	v_mfma_f32_16x16x32_bf16 v[140:143], v[178:181], v[194:197], v[140:143]
	v_mfma_f32_16x16x32_bf16 v[136:139], v[186:189], v[194:197], v[136:139]
	v_mfma_f32_16x16x32_bf16 v[116:119], v[178:181], v[202:205], v[116:119]
	v_mfma_f32_16x16x32_bf16 v[108:111], v[186:189], v[202:205], v[108:111]
	v_mfma_f32_16x16x32_bf16 v[88:91], v[178:181], v[218:221], v[88:91]
	v_mfma_f32_16x16x32_bf16 v[84:87], v[186:189], v[218:221], v[84:87]
	v_mfma_f32_16x16x32_bf16 v[72:75], v[178:181], v[230:233], v[72:75]
	v_mfma_f32_16x16x32_bf16 v[68:71], v[186:189], v[230:233], v[68:71]
	s_setprio 0
	s_barrier
	s_add_i32 s70, s51, s38
	v_lshl_add_u64 v[162:163], s[68:69], 0, v[102:103]
	s_mov_b32 m0, s70
	ds_read_b128 v[190:193], v153 offset:16384
	ds_read_b128 v[194:197], v153 offset:17408
	ds_read_b128 v[198:201], v153 offset:18432
	ds_read_b128 v[202:205], v153 offset:19456
	ds_read_b128 v[206:209], v153 offset:20480
	ds_read_b128 v[218:221], v153 offset:21504
	ds_read_b128 v[226:229], v153 offset:22528
	ds_read_b128 v[230:233], v153 offset:23552
	global_load_lds_dwordx4 v[162:163], off
	s_add_i32 m0, s70, 0x2000
	v_lshl_add_u64 v[210:211], s[68:69], 0, v[114:115]
	s_add_u32 s68, s68, s16
	s_addc_u32 s69, s69, s17
	s_add_i32 s70, s58, s38
	global_load_lds_dwordx4 v[210:211], off
	v_lshl_add_u64 v[234:235], s[68:69], 0, v[102:103]
	s_mov_b32 m0, s70
	v_lshl_add_u64 v[236:237], s[68:69], 0, v[114:115]
	global_load_lds_dwordx4 v[234:235], off
	s_add_i32 m0, s70, 0x2000
	v_lshl_add_u64 v[238:239], s[34:35], 0, v[100:101]
	global_load_lds_dwordx4 v[236:237], off
	s_mov_b32 m0, s42
	v_lshl_add_u64 v[240:241], s[34:35], 0, v[112:113]
	global_load_lds_dwordx4 v[238:239], off
	s_mov_b32 m0, s43
	s_nop 0
	global_load_lds_dwordx4 v[240:241], off
	s_waitcnt vmcnt(8)
	s_waitcnt lgkmcnt(0)
	v_mfma_f32_16x16x32_bf16 v[64:67], v[154:157], v[190:193], v[64:67]
	v_mfma_f32_16x16x32_bf16 v[60:63], v[166:169], v[190:193], v[60:63]
	v_mfma_f32_16x16x32_bf16 v[48:51], v[154:157], v[198:201], v[48:51]
	v_mfma_f32_16x16x32_bf16 v[44:47], v[166:169], v[198:201], v[44:47]
	v_mfma_f32_16x16x32_bf16 v[32:35], v[154:157], v[206:209], v[32:35]
	v_mfma_f32_16x16x32_bf16 v[28:31], v[166:169], v[206:209], v[28:31]
	v_mfma_f32_16x16x32_bf16 v[16:19], v[154:157], v[226:229], v[16:19]
	v_mfma_f32_16x16x32_bf16 v[12:15], v[166:169], v[226:229], v[12:15]
	v_mfma_f32_16x16x32_bf16 v[64:67], v[158:161], v[194:197], v[64:67]
	v_mfma_f32_16x16x32_bf16 v[60:63], v[170:173], v[194:197], v[60:63]
	v_mfma_f32_16x16x32_bf16 v[48:51], v[158:161], v[202:205], v[48:51]
	v_mfma_f32_16x16x32_bf16 v[44:47], v[170:173], v[202:205], v[44:47]
	v_mfma_f32_16x16x32_bf16 v[32:35], v[158:161], v[218:221], v[32:35]
	v_mfma_f32_16x16x32_bf16 v[28:31], v[170:173], v[218:221], v[28:31]
	v_mfma_f32_16x16x32_bf16 v[16:19], v[158:161], v[230:233], v[16:19]
	v_mfma_f32_16x16x32_bf16 v[12:15], v[170:173], v[230:233], v[12:15]
	s_barrier
	s_setprio 1
	s_waitcnt lgkmcnt(0)
	v_mfma_f32_16x16x32_bf16 v[56:59], v[174:177], v[190:193], v[56:59]
	v_mfma_f32_16x16x32_bf16 v[52:55], v[182:185], v[190:193], v[52:55]
	v_mfma_f32_16x16x32_bf16 v[40:43], v[174:177], v[198:201], v[40:43]
	v_mfma_f32_16x16x32_bf16 v[36:39], v[182:185], v[198:201], v[36:39]
	v_mfma_f32_16x16x32_bf16 v[24:27], v[174:177], v[206:209], v[24:27]
	v_mfma_f32_16x16x32_bf16 v[20:23], v[182:185], v[206:209], v[20:23]
	v_mfma_f32_16x16x32_bf16 v[8:11], v[174:177], v[226:229], v[8:11]
	v_mfma_f32_16x16x32_bf16 v[4:7], v[182:185], v[226:229], v[4:7]
	v_mfma_f32_16x16x32_bf16 v[56:59], v[178:181], v[194:197], v[56:59]
	v_mfma_f32_16x16x32_bf16 v[52:55], v[186:189], v[194:197], v[52:55]
	v_mfma_f32_16x16x32_bf16 v[40:43], v[178:181], v[202:205], v[40:43]
	v_mfma_f32_16x16x32_bf16 v[36:39], v[186:189], v[202:205], v[36:39]
	v_mfma_f32_16x16x32_bf16 v[24:27], v[178:181], v[218:221], v[24:27]
	v_mfma_f32_16x16x32_bf16 v[20:23], v[186:189], v[218:221], v[20:23]
	v_mfma_f32_16x16x32_bf16 v[8:11], v[178:181], v[230:233], v[8:11]
	v_mfma_f32_16x16x32_bf16 v[4:7], v[186:189], v[230:233], v[4:7]
	s_setprio 0
	s_barrier
	s_add_i32 s68, 0, 0x18000
	v_add_u32_e32 v93, s68, v152
	s_add_i32 s69, 0, 0x1c000
	ds_read_b128 v[154:157], v93
	ds_read_b128 v[158:161], v93 offset:1024
	ds_read_b128 v[166:169], v93 offset:2048
	ds_read_b128 v[170:173], v93 offset:3072
	v_add_u32_e32 v93, s69, v152
	ds_read_b128 v[174:177], v93
	ds_read_b128 v[178:181], v93 offset:1024
	ds_read_b128 v[182:185], v93 offset:2048
	ds_read_b128 v[186:189], v93 offset:3072
	s_add_u32 s34, s34, s16
	s_addc_u32 s35, s35, s17
	s_mov_b32 m0, s44
	v_lshl_add_u64 v[98:99], s[34:35], 0, v[100:101]
	ds_read_b128 v[190:193], v153 offset:32768
	ds_read_b128 v[194:197], v153 offset:33792
	ds_read_b128 v[198:201], v153 offset:34816
	ds_read_b128 v[202:205], v153 offset:35840
	ds_read_b128 v[206:209], v153 offset:36864
	ds_read_b128 v[218:221], v153 offset:37888
	ds_read_b128 v[226:229], v153 offset:38912
	ds_read_b128 v[230:233], v153 offset:39936
	global_load_lds_dwordx4 v[98:99], off
	v_lshl_add_u64 v[98:99], s[34:35], 0, v[112:113]
	s_mov_b32 m0, s45
	s_nop 0
	global_load_lds_dwordx4 v[98:99], off
	s_waitcnt vmcnt(8)
	s_waitcnt lgkmcnt(0)
	v_mfma_f32_16x16x32_bf16 v[148:151], v[154:157], v[190:193], v[148:151]
	v_mfma_f32_16x16x32_bf16 v[144:147], v[166:169], v[190:193], v[144:147]
	v_mfma_f32_16x16x32_bf16 v[128:131], v[154:157], v[198:201], v[128:131]
	v_mfma_f32_16x16x32_bf16 v[124:127], v[166:169], v[198:201], v[124:127]
	v_mfma_f32_16x16x32_bf16 v[104:107], v[154:157], v[206:209], v[104:107]
	v_mfma_f32_16x16x32_bf16 v[94:97], v[166:169], v[206:209], v[94:97]
	v_mfma_f32_16x16x32_bf16 v[80:83], v[154:157], v[226:229], v[80:83]
	v_mfma_f32_16x16x32_bf16 v[76:79], v[166:169], v[226:229], v[76:79]
	v_mfma_f32_16x16x32_bf16 v[148:151], v[158:161], v[194:197], v[148:151]
	v_mfma_f32_16x16x32_bf16 v[144:147], v[170:173], v[194:197], v[144:147]
	v_mfma_f32_16x16x32_bf16 v[128:131], v[158:161], v[202:205], v[128:131]
	v_mfma_f32_16x16x32_bf16 v[124:127], v[170:173], v[202:205], v[124:127]
	v_mfma_f32_16x16x32_bf16 v[104:107], v[158:161], v[218:221], v[104:107]
	v_mfma_f32_16x16x32_bf16 v[96:99], v[170:173], v[218:221], v[94:97]
	v_mfma_f32_16x16x32_bf16 v[80:83], v[158:161], v[230:233], v[80:83]
	v_mfma_f32_16x16x32_bf16 v[76:79], v[170:173], v[230:233], v[76:79]
	s_barrier
	s_setprio 1
	s_waitcnt lgkmcnt(0)
	v_mfma_f32_16x16x32_bf16 v[140:143], v[174:177], v[190:193], v[140:143]
	v_mfma_f32_16x16x32_bf16 v[136:139], v[182:185], v[190:193], v[136:139]
	v_mfma_f32_16x16x32_bf16 v[116:119], v[174:177], v[198:201], v[116:119]
	v_mfma_f32_16x16x32_bf16 v[108:111], v[182:185], v[198:201], v[108:111]
	v_mfma_f32_16x16x32_bf16 v[88:91], v[174:177], v[206:209], v[88:91]
	v_mfma_f32_16x16x32_bf16 v[84:87], v[182:185], v[206:209], v[84:87]
	v_mfma_f32_16x16x32_bf16 v[72:75], v[174:177], v[226:229], v[72:75]
	v_mfma_f32_16x16x32_bf16 v[68:71], v[182:185], v[226:229], v[68:71]
	v_mfma_f32_16x16x32_bf16 v[140:143], v[178:181], v[194:197], v[140:143]
	v_mfma_f32_16x16x32_bf16 v[136:139], v[186:189], v[194:197], v[136:139]
	v_mfma_f32_16x16x32_bf16 v[116:119], v[178:181], v[202:205], v[116:119]
	v_mfma_f32_16x16x32_bf16 v[108:111], v[186:189], v[202:205], v[108:111]
	v_mfma_f32_16x16x32_bf16 v[88:91], v[178:181], v[218:221], v[88:91]
	v_mfma_f32_16x16x32_bf16 v[84:87], v[186:189], v[218:221], v[84:87]
	v_mfma_f32_16x16x32_bf16 v[72:75], v[178:181], v[230:233], v[72:75]
	v_mfma_f32_16x16x32_bf16 v[68:71], v[186:189], v[230:233], v[68:71]
	s_setprio 0
	s_barrier
	s_add_i32 s34, s68, s38
	v_lshl_add_u64 v[94:95], v[162:163], 0, s[24:25]
	s_mov_b32 m0, s34
	ds_read_b128 v[190:193], v153 offset:49152
	ds_read_b128 v[194:197], v153 offset:50176
	ds_read_b128 v[198:201], v153 offset:51200
	ds_read_b128 v[202:205], v153 offset:52224
	ds_read_b128 v[206:209], v153 offset:53248
	ds_read_b128 v[218:221], v153 offset:54272
	ds_read_b128 v[226:229], v153 offset:55296
	ds_read_b128 v[230:233], v153 offset:56320
	global_load_lds_dwordx4 v[94:95], off
	v_lshl_add_u64 v[94:95], v[210:211], 0, s[24:25]
	s_add_i32 m0, s34, 0x2000
	s_add_i32 s34, s69, s38
	global_load_lds_dwordx4 v[94:95], off
	v_lshl_add_u64 v[94:95], v[234:235], 0, s[24:25]
	s_mov_b32 m0, s34
	s_nop 0
	global_load_lds_dwordx4 v[94:95], off
	v_lshl_add_u64 v[94:95], v[236:237], 0, s[24:25]
	s_add_i32 m0, s34, 0x2000
	s_nop 0
	global_load_lds_dwordx4 v[94:95], off
	v_lshl_add_u64 v[94:95], v[238:239], 0, s[24:25]
	s_mov_b32 m0, s46
	s_nop 0
	global_load_lds_dwordx4 v[94:95], off
	v_lshl_add_u64 v[94:95], v[240:241], 0, s[24:25]
	s_mov_b32 m0, s47
	s_nop 0
	global_load_lds_dwordx4 v[94:95], off
	s_waitcnt vmcnt(8)
	s_waitcnt lgkmcnt(0)
	v_mfma_f32_16x16x32_bf16 v[64:67], v[154:157], v[190:193], v[64:67]
	v_mfma_f32_16x16x32_bf16 v[60:63], v[166:169], v[190:193], v[60:63]
	v_mfma_f32_16x16x32_bf16 v[48:51], v[154:157], v[198:201], v[48:51]
	v_mfma_f32_16x16x32_bf16 v[44:47], v[166:169], v[198:201], v[44:47]
	v_mfma_f32_16x16x32_bf16 v[32:35], v[154:157], v[206:209], v[32:35]
	v_mfma_f32_16x16x32_bf16 v[28:31], v[166:169], v[206:209], v[28:31]
	v_mfma_f32_16x16x32_bf16 v[16:19], v[154:157], v[226:229], v[16:19]
	v_mfma_f32_16x16x32_bf16 v[12:15], v[166:169], v[226:229], v[12:15]
	v_mfma_f32_16x16x32_bf16 v[64:67], v[158:161], v[194:197], v[64:67]
	v_mfma_f32_16x16x32_bf16 v[60:63], v[170:173], v[194:197], v[60:63]
	v_mfma_f32_16x16x32_bf16 v[48:51], v[158:161], v[202:205], v[48:51]
	v_mfma_f32_16x16x32_bf16 v[44:47], v[170:173], v[202:205], v[44:47]
	v_mfma_f32_16x16x32_bf16 v[32:35], v[158:161], v[218:221], v[32:35]
	v_mfma_f32_16x16x32_bf16 v[28:31], v[170:173], v[218:221], v[28:31]
	v_mfma_f32_16x16x32_bf16 v[16:19], v[158:161], v[230:233], v[16:19]
	v_mfma_f32_16x16x32_bf16 v[12:15], v[170:173], v[230:233], v[12:15]
	s_barrier
	s_setprio 1
	s_waitcnt lgkmcnt(0)
	v_mfma_f32_16x16x32_bf16 v[56:59], v[174:177], v[190:193], v[56:59]
	v_mfma_f32_16x16x32_bf16 v[52:55], v[182:185], v[190:193], v[52:55]
	v_mfma_f32_16x16x32_bf16 v[40:43], v[174:177], v[198:201], v[40:43]
	v_mfma_f32_16x16x32_bf16 v[36:39], v[182:185], v[198:201], v[36:39]
	v_mfma_f32_16x16x32_bf16 v[24:27], v[174:177], v[206:209], v[24:27]
	v_mfma_f32_16x16x32_bf16 v[20:23], v[182:185], v[206:209], v[20:23]
	v_mfma_f32_16x16x32_bf16 v[8:11], v[174:177], v[226:229], v[8:11]
	v_mfma_f32_16x16x32_bf16 v[4:7], v[182:185], v[226:229], v[4:7]
	v_mfma_f32_16x16x32_bf16 v[56:59], v[178:181], v[194:197], v[56:59]
	v_mfma_f32_16x16x32_bf16 v[52:55], v[186:189], v[194:197], v[52:55]
	v_mfma_f32_16x16x32_bf16 v[40:43], v[178:181], v[202:205], v[40:43]
	v_mfma_f32_16x16x32_bf16 v[36:39], v[186:189], v[202:205], v[36:39]
	v_mfma_f32_16x16x32_bf16 v[24:27], v[178:181], v[218:221], v[24:27]
	v_mfma_f32_16x16x32_bf16 v[20:23], v[186:189], v[218:221], v[20:23]
	v_mfma_f32_16x16x32_bf16 v[8:11], v[178:181], v[230:233], v[8:11]
	v_mfma_f32_16x16x32_bf16 v[4:7], v[186:189], v[230:233], v[4:7]
	s_setprio 0
	s_barrier
	s_add_u32 s30, s30, 0x100
	s_addc_u32 s31, s31, 0
	s_add_u32 s65, s65, 0x100
	s_addc_u32 s66, s66, 0
	s_cmp_ge_i32 s67, s49
	s_mov_b32 s34, s67
	s_cbranch_scc0 .LBB0_936

.LBB0_1116:
	ds_read_b128 v[148:151], v160
	ds_read_b128 v[152:155], v160 offset:1024
	ds_read_b128 v[166:169], v160 offset:2048
	ds_read_b128 v[170:173], v160 offset:3072
	ds_read_b128 v[174:177], v161
	ds_read_b128 v[178:181], v161 offset:1024
	ds_read_b128 v[182:185], v161 offset:2048
	ds_read_b128 v[186:189], v161 offset:3072
	s_add_u32 s48, s4, 0xfffc0080
	s_addc_u32 s49, s5, -1
	s_cmp_eq_u32 s71, 12
	s_cselect_b32 s59, s39, s49
	s_cselect_b32 s58, s45, s48
	s_cselect_b32 s49, s37, s70
	s_cselect_b32 s48, s60, s61
	v_lshl_add_u64 v[210:211], s[4:5], 0, v[140:141]
	s_add_i32 m0, s47, 0xc000
	ds_read_b128 v[190:193], v162
	ds_read_b128 v[194:197], v162 offset:1024
	ds_read_b128 v[198:201], v162 offset:2048
	ds_read_b128 v[202:205], v162 offset:3072
	ds_read_b128 v[206:209], v162 offset:4096
	ds_read_b128 v[226:229], v162 offset:5120
	ds_read_b128 v[230:233], v162 offset:6144
	ds_read_b128 v[234:237], v162 offset:7168
	global_load_lds_dwordx4 v[210:211], off
	v_lshl_add_u64 v[210:211], s[4:5], 0, v[142:143]
	s_add_i32 m0, s47, 0xe000
	s_nop 0
	global_load_lds_dwordx4 v[210:211], off
	s_waitcnt vmcnt(8)
	s_waitcnt lgkmcnt(0)
	v_mfma_f32_16x16x32_bf16 v[128:131], v[148:151], v[190:193], v[128:131]
	v_mfma_f32_16x16x32_bf16 v[124:127], v[166:169], v[190:193], v[124:127]
	v_mfma_f32_16x16x32_bf16 v[112:115], v[148:151], v[198:201], v[112:115]
	v_mfma_f32_16x16x32_bf16 v[108:111], v[166:169], v[198:201], v[108:111]
	v_mfma_f32_16x16x32_bf16 v[96:99], v[148:151], v[206:209], v[96:99]
	v_mfma_f32_16x16x32_bf16 v[92:95], v[166:169], v[206:209], v[92:95]
	v_mfma_f32_16x16x32_bf16 v[80:83], v[148:151], v[230:233], v[80:83]
	v_mfma_f32_16x16x32_bf16 v[76:79], v[166:169], v[230:233], v[76:79]
	v_mfma_f32_16x16x32_bf16 v[128:131], v[152:155], v[194:197], v[128:131]
	v_mfma_f32_16x16x32_bf16 v[124:127], v[170:173], v[194:197], v[124:127]
	v_mfma_f32_16x16x32_bf16 v[112:115], v[152:155], v[202:205], v[112:115]
	v_mfma_f32_16x16x32_bf16 v[108:111], v[170:173], v[202:205], v[108:111]
	v_mfma_f32_16x16x32_bf16 v[96:99], v[152:155], v[226:229], v[96:99]
	v_mfma_f32_16x16x32_bf16 v[92:95], v[170:173], v[226:229], v[92:95]
	v_mfma_f32_16x16x32_bf16 v[80:83], v[152:155], v[234:237], v[80:83]
	v_mfma_f32_16x16x32_bf16 v[76:79], v[170:173], v[234:237], v[76:79]
	s_barrier
	s_setprio 1
	s_waitcnt lgkmcnt(0)
	v_mfma_f32_16x16x32_bf16 v[120:123], v[174:177], v[190:193], v[120:123]
	v_mfma_f32_16x16x32_bf16 v[116:119], v[182:185], v[190:193], v[116:119]
	v_mfma_f32_16x16x32_bf16 v[104:107], v[174:177], v[198:201], v[104:107]
	v_mfma_f32_16x16x32_bf16 v[100:103], v[182:185], v[198:201], v[100:103]
	v_mfma_f32_16x16x32_bf16 v[88:91], v[174:177], v[206:209], v[88:91]
	v_mfma_f32_16x16x32_bf16 v[84:87], v[182:185], v[206:209], v[84:87]
	v_mfma_f32_16x16x32_bf16 v[72:75], v[174:177], v[230:233], v[72:75]
	v_mfma_f32_16x16x32_bf16 v[68:71], v[182:185], v[230:233], v[68:71]
	v_mfma_f32_16x16x32_bf16 v[120:123], v[178:181], v[194:197], v[120:123]
	v_mfma_f32_16x16x32_bf16 v[116:119], v[186:189], v[194:197], v[116:119]
	v_mfma_f32_16x16x32_bf16 v[104:107], v[178:181], v[202:205], v[104:107]
	v_mfma_f32_16x16x32_bf16 v[100:103], v[186:189], v[202:205], v[100:103]
	v_mfma_f32_16x16x32_bf16 v[88:91], v[178:181], v[226:229], v[88:91]
	v_mfma_f32_16x16x32_bf16 v[84:87], v[186:189], v[226:229], v[84:87]
	v_mfma_f32_16x16x32_bf16 v[72:75], v[178:181], v[234:237], v[72:75]
	v_mfma_f32_16x16x32_bf16 v[68:71], v[186:189], v[234:237], v[68:71]
	s_setprio 0
	s_barrier
	s_add_i32 s72, s78, s3
	v_lshl_add_u64 v[210:211], s[48:49], 0, v[134:135]
	s_mov_b32 m0, s72
	ds_read_b128 v[190:193], v162 offset:16384
	ds_read_b128 v[194:197], v162 offset:17408
	ds_read_b128 v[198:201], v162 offset:18432
	ds_read_b128 v[202:205], v162 offset:19456
	ds_read_b128 v[206:209], v162 offset:20480
	ds_read_b128 v[226:229], v162 offset:21504
	ds_read_b128 v[230:233], v162 offset:22528
	ds_read_b128 v[234:237], v162 offset:23552
	global_load_lds_dwordx4 v[210:211], off
	s_add_i32 m0, s72, 0x2000
	s_add_u32 s72, s48, 0x40000
	v_lshl_add_u64 v[220:221], s[48:49], 0, v[138:139]
	s_addc_u32 s73, s49, 0
	s_add_i32 s74, s79, s3
	global_load_lds_dwordx4 v[220:221], off
	v_lshl_add_u64 v[238:239], s[72:73], 0, v[134:135]
	s_mov_b32 m0, s74
	v_lshl_add_u64 v[240:241], s[58:59], 0, v[136:137]
	global_load_lds_dwordx4 v[238:239], off
	v_lshl_add_u64 v[238:239], s[72:73], 0, v[138:139]
	s_add_i32 m0, s74, 0x2000
	s_nop 0
	global_load_lds_dwordx4 v[238:239], off
	v_lshl_add_u64 v[238:239], s[58:59], 0, v[132:133]
	s_mov_b32 m0, s47
	s_nop 0
	global_load_lds_dwordx4 v[238:239], off
	s_mov_b32 m0, s51
	s_nop 0
	global_load_lds_dwordx4 v[240:241], off
	s_waitcnt vmcnt(8)
	s_waitcnt lgkmcnt(0)
	v_mfma_f32_16x16x32_bf16 v[64:67], v[148:151], v[190:193], v[64:67]
	v_mfma_f32_16x16x32_bf16 v[60:63], v[166:169], v[190:193], v[60:63]
	v_mfma_f32_16x16x32_bf16 v[48:51], v[148:151], v[198:201], v[48:51]
	v_mfma_f32_16x16x32_bf16 v[44:47], v[166:169], v[198:201], v[44:47]
	v_mfma_f32_16x16x32_bf16 v[32:35], v[148:151], v[206:209], v[32:35]
	v_mfma_f32_16x16x32_bf16 v[28:31], v[166:169], v[206:209], v[28:31]
	v_mfma_f32_16x16x32_bf16 v[16:19], v[148:151], v[230:233], v[16:19]
	v_mfma_f32_16x16x32_bf16 v[12:15], v[166:169], v[230:233], v[12:15]
	v_mfma_f32_16x16x32_bf16 v[64:67], v[152:155], v[194:197], v[64:67]
	v_mfma_f32_16x16x32_bf16 v[60:63], v[170:173], v[194:197], v[60:63]
	v_mfma_f32_16x16x32_bf16 v[48:51], v[152:155], v[202:205], v[48:51]
	v_mfma_f32_16x16x32_bf16 v[44:47], v[170:173], v[202:205], v[44:47]
	v_mfma_f32_16x16x32_bf16 v[32:35], v[152:155], v[226:229], v[32:35]
	v_mfma_f32_16x16x32_bf16 v[28:31], v[170:173], v[226:229], v[28:31]
	v_mfma_f32_16x16x32_bf16 v[16:19], v[152:155], v[234:237], v[16:19]
	v_mfma_f32_16x16x32_bf16 v[12:15], v[170:173], v[234:237], v[12:15]
	s_barrier
	s_setprio 1
	s_waitcnt lgkmcnt(0)
	v_mfma_f32_16x16x32_bf16 v[56:59], v[174:177], v[190:193], v[56:59]
	v_mfma_f32_16x16x32_bf16 v[52:55], v[182:185], v[190:193], v[52:55]
	v_mfma_f32_16x16x32_bf16 v[40:43], v[174:177], v[198:201], v[40:43]
	v_mfma_f32_16x16x32_bf16 v[36:39], v[182:185], v[198:201], v[36:39]
	v_mfma_f32_16x16x32_bf16 v[24:27], v[174:177], v[206:209], v[24:27]
	v_mfma_f32_16x16x32_bf16 v[20:23], v[182:185], v[206:209], v[20:23]
	v_mfma_f32_16x16x32_bf16 v[8:11], v[174:177], v[230:233], v[8:11]
	v_mfma_f32_16x16x32_bf16 v[4:7], v[182:185], v[230:233], v[4:7]
	v_mfma_f32_16x16x32_bf16 v[56:59], v[178:181], v[194:197], v[56:59]
	v_mfma_f32_16x16x32_bf16 v[52:55], v[186:189], v[194:197], v[52:55]
	v_mfma_f32_16x16x32_bf16 v[40:43], v[178:181], v[202:205], v[40:43]
	v_mfma_f32_16x16x32_bf16 v[36:39], v[186:189], v[202:205], v[36:39]
	v_mfma_f32_16x16x32_bf16 v[24:27], v[178:181], v[226:229], v[24:27]
	v_mfma_f32_16x16x32_bf16 v[20:23], v[186:189], v[226:229], v[20:23]
	v_mfma_f32_16x16x32_bf16 v[8:11], v[178:181], v[234:237], v[8:11]
	v_mfma_f32_16x16x32_bf16 v[4:7], v[186:189], v[234:237], v[4:7]
	s_setprio 0
	s_barrier
	s_add_i32 s72, 0, 0x18000
	v_add_u32_e32 v165, s72, v3
	s_add_i32 s73, 0, 0x1c000
	ds_read_b128 v[148:151], v165
	ds_read_b128 v[152:155], v165 offset:1024
	ds_read_b128 v[166:169], v165 offset:2048
	ds_read_b128 v[170:173], v165 offset:3072
	v_add_u32_e32 v165, s73, v3
	ds_read_b128 v[174:177], v165
	ds_read_b128 v[178:181], v165 offset:1024
	ds_read_b128 v[182:185], v165 offset:2048
	ds_read_b128 v[186:189], v165 offset:3072
	s_add_u32 s58, s58, 0x40000
	s_addc_u32 s59, s59, 0
	s_mov_b32 m0, s64
	v_lshl_add_u64 v[242:243], s[58:59], 0, v[132:133]
	ds_read_b128 v[190:193], v162 offset:32768
	ds_read_b128 v[194:197], v162 offset:33792
	ds_read_b128 v[198:201], v162 offset:34816
	ds_read_b128 v[202:205], v162 offset:35840
	ds_read_b128 v[206:209], v162 offset:36864
	ds_read_b128 v[226:229], v162 offset:37888
	ds_read_b128 v[230:233], v162 offset:38912
	ds_read_b128 v[234:237], v162 offset:39936
	global_load_lds_dwordx4 v[242:243], off
	v_lshl_add_u64 v[242:243], s[58:59], 0, v[136:137]
	s_mov_b32 m0, s65
	s_nop 0
	global_load_lds_dwordx4 v[242:243], off
	s_waitcnt vmcnt(8)
	s_waitcnt lgkmcnt(0)
	v_mfma_f32_16x16x32_bf16 v[128:131], v[148:151], v[190:193], v[128:131]
	v_mfma_f32_16x16x32_bf16 v[124:127], v[166:169], v[190:193], v[124:127]
	v_mfma_f32_16x16x32_bf16 v[112:115], v[148:151], v[198:201], v[112:115]
	v_mfma_f32_16x16x32_bf16 v[108:111], v[166:169], v[198:201], v[108:111]
	v_mfma_f32_16x16x32_bf16 v[96:99], v[148:151], v[206:209], v[96:99]
	v_mfma_f32_16x16x32_bf16 v[92:95], v[166:169], v[206:209], v[92:95]
	v_mfma_f32_16x16x32_bf16 v[80:83], v[148:151], v[230:233], v[80:83]
	v_mfma_f32_16x16x32_bf16 v[76:79], v[166:169], v[230:233], v[76:79]
	v_mfma_f32_16x16x32_bf16 v[128:131], v[152:155], v[194:197], v[128:131]
	v_mfma_f32_16x16x32_bf16 v[124:127], v[170:173], v[194:197], v[124:127]
	v_mfma_f32_16x16x32_bf16 v[112:115], v[152:155], v[202:205], v[112:115]
	v_mfma_f32_16x16x32_bf16 v[108:111], v[170:173], v[202:205], v[108:111]
	v_mfma_f32_16x16x32_bf16 v[96:99], v[152:155], v[226:229], v[96:99]
	v_mfma_f32_16x16x32_bf16 v[92:95], v[170:173], v[226:229], v[92:95]
	v_mfma_f32_16x16x32_bf16 v[80:83], v[152:155], v[234:237], v[80:83]
	v_mfma_f32_16x16x32_bf16 v[76:79], v[170:173], v[234:237], v[76:79]
	s_barrier
	s_setprio 1
	s_waitcnt lgkmcnt(0)
	v_mfma_f32_16x16x32_bf16 v[120:123], v[174:177], v[190:193], v[120:123]
	v_mfma_f32_16x16x32_bf16 v[116:119], v[182:185], v[190:193], v[116:119]
	v_mfma_f32_16x16x32_bf16 v[104:107], v[174:177], v[198:201], v[104:107]
	v_mfma_f32_16x16x32_bf16 v[100:103], v[182:185], v[198:201], v[100:103]
	v_mfma_f32_16x16x32_bf16 v[88:91], v[174:177], v[206:209], v[88:91]
	v_mfma_f32_16x16x32_bf16 v[84:87], v[182:185], v[206:209], v[84:87]
	v_mfma_f32_16x16x32_bf16 v[72:75], v[174:177], v[230:233], v[72:75]
	v_mfma_f32_16x16x32_bf16 v[68:71], v[182:185], v[230:233], v[68:71]
	v_mfma_f32_16x16x32_bf16 v[120:123], v[178:181], v[194:197], v[120:123]
	v_mfma_f32_16x16x32_bf16 v[116:119], v[186:189], v[194:197], v[116:119]
	v_mfma_f32_16x16x32_bf16 v[104:107], v[178:181], v[202:205], v[104:107]
	v_mfma_f32_16x16x32_bf16 v[100:103], v[186:189], v[202:205], v[100:103]
	v_mfma_f32_16x16x32_bf16 v[88:91], v[178:181], v[226:229], v[88:91]
	v_mfma_f32_16x16x32_bf16 v[84:87], v[186:189], v[226:229], v[84:87]
	v_mfma_f32_16x16x32_bf16 v[72:75], v[178:181], v[234:237], v[72:75]
	v_mfma_f32_16x16x32_bf16 v[68:71], v[186:189], v[234:237], v[68:71]
	s_setprio 0
	s_barrier
	s_add_i32 s58, s72, s3
	v_lshl_add_u64 v[210:211], v[210:211], 0, s[22:23]
	s_mov_b32 m0, s58
	ds_read_b128 v[190:193], v162 offset:49152
	ds_read_b128 v[194:197], v162 offset:50176
	ds_read_b128 v[198:201], v162 offset:51200
	ds_read_b128 v[202:205], v162 offset:52224
	ds_read_b128 v[206:209], v162 offset:53248
	ds_read_b128 v[226:229], v162 offset:54272
	ds_read_b128 v[230:233], v162 offset:55296
	ds_read_b128 v[234:237], v162 offset:56320
	global_load_lds_dwordx4 v[210:211], off
	s_add_i32 m0, s58, 0x2000
	s_add_u32 s48, s48, 0x40080
	v_lshl_add_u64 v[210:211], v[220:221], 0, s[22:23]
	s_addc_u32 s49, s49, 0
	s_add_i32 s58, s73, s3
	global_load_lds_dwordx4 v[210:211], off
	v_lshl_add_u64 v[210:211], s[48:49], 0, v[134:135]
	s_mov_b32 m0, s58
	s_nop 0
	global_load_lds_dwordx4 v[210:211], off
	v_lshl_add_u64 v[210:211], s[48:49], 0, v[138:139]
	s_add_i32 m0, s58, 0x2000
	s_nop 0
	global_load_lds_dwordx4 v[210:211], off
	v_lshl_add_u64 v[210:211], v[238:239], 0, s[22:23]
	s_mov_b32 m0, s68
	s_nop 0
	global_load_lds_dwordx4 v[210:211], off
	v_lshl_add_u64 v[210:211], v[240:241], 0, s[22:23]
	s_mov_b32 m0, s69
	s_nop 0
	global_load_lds_dwordx4 v[210:211], off
	s_waitcnt vmcnt(8)
	s_waitcnt lgkmcnt(0)
	v_mfma_f32_16x16x32_bf16 v[64:67], v[148:151], v[190:193], v[64:67]
	v_mfma_f32_16x16x32_bf16 v[60:63], v[166:169], v[190:193], v[60:63]
	v_mfma_f32_16x16x32_bf16 v[48:51], v[148:151], v[198:201], v[48:51]
	v_mfma_f32_16x16x32_bf16 v[44:47], v[166:169], v[198:201], v[44:47]
	v_mfma_f32_16x16x32_bf16 v[32:35], v[148:151], v[206:209], v[32:35]
	v_mfma_f32_16x16x32_bf16 v[28:31], v[166:169], v[206:209], v[28:31]
	v_mfma_f32_16x16x32_bf16 v[16:19], v[148:151], v[230:233], v[16:19]
	v_mfma_f32_16x16x32_bf16 v[12:15], v[166:169], v[230:233], v[12:15]
	v_mfma_f32_16x16x32_bf16 v[64:67], v[152:155], v[194:197], v[64:67]
	v_mfma_f32_16x16x32_bf16 v[60:63], v[170:173], v[194:197], v[60:63]
	v_mfma_f32_16x16x32_bf16 v[48:51], v[152:155], v[202:205], v[48:51]
	v_mfma_f32_16x16x32_bf16 v[44:47], v[170:173], v[202:205], v[44:47]
	v_mfma_f32_16x16x32_bf16 v[32:35], v[152:155], v[226:229], v[32:35]
	v_mfma_f32_16x16x32_bf16 v[28:31], v[170:173], v[226:229], v[28:31]
	v_mfma_f32_16x16x32_bf16 v[16:19], v[152:155], v[234:237], v[16:19]
	v_mfma_f32_16x16x32_bf16 v[12:15], v[170:173], v[234:237], v[12:15]
	s_barrier
	s_setprio 1
	s_waitcnt lgkmcnt(0)
	v_mfma_f32_16x16x32_bf16 v[56:59], v[174:177], v[190:193], v[56:59]
	v_mfma_f32_16x16x32_bf16 v[52:55], v[182:185], v[190:193], v[52:55]
	v_mfma_f32_16x16x32_bf16 v[40:43], v[174:177], v[198:201], v[40:43]
	v_mfma_f32_16x16x32_bf16 v[36:39], v[182:185], v[198:201], v[36:39]
	v_mfma_f32_16x16x32_bf16 v[24:27], v[174:177], v[206:209], v[24:27]
	v_mfma_f32_16x16x32_bf16 v[20:23], v[182:185], v[206:209], v[20:23]
	v_mfma_f32_16x16x32_bf16 v[8:11], v[174:177], v[230:233], v[8:11]
	v_mfma_f32_16x16x32_bf16 v[4:7], v[182:185], v[230:233], v[4:7]
	v_mfma_f32_16x16x32_bf16 v[56:59], v[178:181], v[194:197], v[56:59]
	v_mfma_f32_16x16x32_bf16 v[52:55], v[186:189], v[194:197], v[52:55]
	v_mfma_f32_16x16x32_bf16 v[40:43], v[178:181], v[202:205], v[40:43]
	v_mfma_f32_16x16x32_bf16 v[36:39], v[186:189], v[202:205], v[36:39]
	v_mfma_f32_16x16x32_bf16 v[24:27], v[178:181], v[226:229], v[24:27]
	v_mfma_f32_16x16x32_bf16 v[20:23], v[186:189], v[226:229], v[20:23]
	v_mfma_f32_16x16x32_bf16 v[8:11], v[178:181], v[234:237], v[8:11]
	v_mfma_f32_16x16x32_bf16 v[4:7], v[186:189], v[234:237], v[4:7]
	s_setprio 0
	s_barrier
	s_add_i32 s71, s71, 2
	s_add_u32 s4, s4, 0x100
	s_addc_u32 s5, s5, 0
	s_add_u32 s61, s61, 0x100
	s_addc_u32 s70, s70, 0
	s_cmp_gt_u32 s71, 13
	s_cbranch_scc0 .LBB0_1116
	s_and_b64 vcc, exec, s[24:25]
	s_cbranch_vccz .LBB0_1119
	s_barrier

.LBB0_1612:
	v_add_u32_e32 v160, s46, v150
	ds_read_b128 v[152:155], v160
	ds_read_b128 v[156:159], v160 offset:1024
	ds_read_b128 v[166:169], v160 offset:2048
	ds_read_b128 v[170:173], v160 offset:3072
	v_add_u32_e32 v160, s47, v150
	s_add_u32 s28, s14, s26
	ds_read_b128 v[174:177], v160
	ds_read_b128 v[178:181], v160 offset:1024
	ds_read_b128 v[182:185], v160 offset:2048
	ds_read_b128 v[186:189], v160 offset:3072
	s_addc_u32 s29, s15, s27
	s_add_u32 s28, s28, 0x100
	s_addc_u32 s29, s29, 0
	s_add_u32 s60, s49, s26
	s_addc_u32 s61, s50, s27
	s_cmpk_eq_i32 s26, 0x700
	s_cselect_b32 s31, s21, s29
	s_cselect_b32 s30, s51, s28
	s_cselect_b32 s29, s19, s61
	s_cselect_b32 s28, s58, s60
	v_lshl_add_u64 v[160:161], v[146:147], 0, s[26:27]
	s_add_i32 m0, s38, 0xc000
	ds_read_b128 v[190:193], v151
	ds_read_b128 v[194:197], v151 offset:1024
	ds_read_b128 v[198:201], v151 offset:2048
	ds_read_b128 v[202:205], v151 offset:3072
	ds_read_b128 v[206:209], v151 offset:4096
	ds_read_b128 v[226:229], v151 offset:5120
	ds_read_b128 v[230:233], v151 offset:6144
	ds_read_b128 v[234:237], v151 offset:7168
	global_load_lds_dwordx4 v[160:161], off
	v_lshl_add_u64 v[160:161], v[148:149], 0, s[26:27]
	s_add_i32 m0, s38, 0xe000
	s_nop 0
	global_load_lds_dwordx4 v[160:161], off
	s_waitcnt vmcnt(8)
	s_waitcnt lgkmcnt(0)
	v_mfma_f32_16x16x32_bf16 v[122:125], v[152:155], v[190:193], v[122:125]
	v_mfma_f32_16x16x32_bf16 v[126:129], v[166:169], v[190:193], v[126:129]
	v_mfma_f32_16x16x32_bf16 v[110:113], v[152:155], v[198:201], v[110:113]
	v_mfma_f32_16x16x32_bf16 v[106:109], v[166:169], v[198:201], v[106:109]
	v_mfma_f32_16x16x32_bf16 v[94:97], v[152:155], v[206:209], v[94:97]
	v_mfma_f32_16x16x32_bf16 v[90:93], v[166:169], v[206:209], v[90:93]
	v_mfma_f32_16x16x32_bf16 v[78:81], v[152:155], v[230:233], v[78:81]
	v_mfma_f32_16x16x32_bf16 v[74:77], v[166:169], v[230:233], v[74:77]
	v_mfma_f32_16x16x32_bf16 v[122:125], v[156:159], v[194:197], v[122:125]
	v_mfma_f32_16x16x32_bf16 v[126:129], v[170:173], v[194:197], v[126:129]
	v_mfma_f32_16x16x32_bf16 v[110:113], v[156:159], v[202:205], v[110:113]
	v_mfma_f32_16x16x32_bf16 v[106:109], v[170:173], v[202:205], v[106:109]
	v_mfma_f32_16x16x32_bf16 v[94:97], v[156:159], v[226:229], v[94:97]
	v_mfma_f32_16x16x32_bf16 v[90:93], v[170:173], v[226:229], v[90:93]
	v_mfma_f32_16x16x32_bf16 v[78:81], v[156:159], v[234:237], v[78:81]
	v_mfma_f32_16x16x32_bf16 v[74:77], v[170:173], v[234:237], v[74:77]
	s_barrier
	s_setprio 1
	s_waitcnt lgkmcnt(0)
	v_mfma_f32_16x16x32_bf16 v[118:121], v[174:177], v[190:193], v[118:121]
	v_mfma_f32_16x16x32_bf16 v[114:117], v[182:185], v[190:193], v[114:117]
	v_mfma_f32_16x16x32_bf16 v[102:105], v[174:177], v[198:201], v[102:105]
	v_mfma_f32_16x16x32_bf16 v[98:101], v[182:185], v[198:201], v[98:101]
	v_mfma_f32_16x16x32_bf16 v[86:89], v[174:177], v[206:209], v[86:89]
	v_mfma_f32_16x16x32_bf16 v[82:85], v[182:185], v[206:209], v[82:85]
	v_mfma_f32_16x16x32_bf16 v[70:73], v[174:177], v[230:233], v[70:73]
	v_mfma_f32_16x16x32_bf16 v[66:69], v[182:185], v[230:233], v[66:69]
	v_mfma_f32_16x16x32_bf16 v[118:121], v[178:181], v[194:197], v[118:121]
	v_mfma_f32_16x16x32_bf16 v[114:117], v[186:189], v[194:197], v[114:117]
	v_mfma_f32_16x16x32_bf16 v[102:105], v[178:181], v[202:205], v[102:105]
	v_mfma_f32_16x16x32_bf16 v[98:101], v[186:189], v[202:205], v[98:101]
	v_mfma_f32_16x16x32_bf16 v[86:89], v[178:181], v[226:229], v[86:89]
	v_mfma_f32_16x16x32_bf16 v[82:85], v[186:189], v[226:229], v[82:85]
	v_mfma_f32_16x16x32_bf16 v[70:73], v[178:181], v[234:237], v[70:73]
	v_mfma_f32_16x16x32_bf16 v[66:69], v[186:189], v[234:237], v[66:69]
	s_setprio 0
	s_barrier
	s_add_i32 s60, s46, s37
	v_lshl_add_u64 v[160:161], s[28:29], 0, v[132:133]
	s_mov_b32 m0, s60
	ds_read_b128 v[190:193], v151 offset:16384
	ds_read_b128 v[194:197], v151 offset:17408
	ds_read_b128 v[198:201], v151 offset:18432
	ds_read_b128 v[202:205], v151 offset:19456
	ds_read_b128 v[206:209], v151 offset:20480
	ds_read_b128 v[226:229], v151 offset:21504
	ds_read_b128 v[230:233], v151 offset:22528
	ds_read_b128 v[234:237], v151 offset:23552
	global_load_lds_dwordx4 v[160:161], off
	s_add_i32 m0, s60, 0x2000
	s_add_u32 s60, s28, 0x40000
	v_lshl_add_u64 v[210:211], s[28:29], 0, v[136:137]
	s_addc_u32 s61, s29, 0
	s_add_i32 s64, s47, s37
	global_load_lds_dwordx4 v[210:211], off
	v_lshl_add_u64 v[214:215], s[60:61], 0, v[132:133]
	s_mov_b32 m0, s64
	v_lshl_add_u64 v[220:221], s[30:31], 0, v[134:135]
	global_load_lds_dwordx4 v[214:215], off
	v_lshl_add_u64 v[214:215], s[60:61], 0, v[136:137]
	s_add_i32 m0, s64, 0x2000
	s_nop 0
	global_load_lds_dwordx4 v[214:215], off
	v_lshl_add_u64 v[214:215], s[30:31], 0, v[130:131]
	s_mov_b32 m0, s38
	s_nop 0
	global_load_lds_dwordx4 v[214:215], off
	s_mov_b32 m0, s39
	s_nop 0
	global_load_lds_dwordx4 v[220:221], off
	s_waitcnt vmcnt(8)
	s_waitcnt lgkmcnt(0)
	v_mfma_f32_16x16x32_bf16 v[62:65], v[152:155], v[190:193], v[62:65]
	v_mfma_f32_16x16x32_bf16 v[58:61], v[166:169], v[190:193], v[58:61]
	v_mfma_f32_16x16x32_bf16 v[46:49], v[152:155], v[198:201], v[46:49]
	v_mfma_f32_16x16x32_bf16 v[42:45], v[166:169], v[198:201], v[42:45]
	v_mfma_f32_16x16x32_bf16 v[30:33], v[152:155], v[206:209], v[30:33]
	v_mfma_f32_16x16x32_bf16 v[26:29], v[166:169], v[206:209], v[26:29]
	v_mfma_f32_16x16x32_bf16 v[14:17], v[152:155], v[230:233], v[14:17]
	v_mfma_f32_16x16x32_bf16 v[10:13], v[166:169], v[230:233], v[10:13]
	v_mfma_f32_16x16x32_bf16 v[62:65], v[156:159], v[194:197], v[62:65]
	v_mfma_f32_16x16x32_bf16 v[58:61], v[170:173], v[194:197], v[58:61]
	v_mfma_f32_16x16x32_bf16 v[46:49], v[156:159], v[202:205], v[46:49]
	v_mfma_f32_16x16x32_bf16 v[42:45], v[170:173], v[202:205], v[42:45]
	v_mfma_f32_16x16x32_bf16 v[30:33], v[156:159], v[226:229], v[30:33]
	v_mfma_f32_16x16x32_bf16 v[26:29], v[170:173], v[226:229], v[26:29]
	v_mfma_f32_16x16x32_bf16 v[14:17], v[156:159], v[234:237], v[14:17]
	v_mfma_f32_16x16x32_bf16 v[10:13], v[170:173], v[234:237], v[10:13]
	s_barrier
	s_setprio 1
	s_waitcnt lgkmcnt(0)
	v_mfma_f32_16x16x32_bf16 v[54:57], v[174:177], v[190:193], v[54:57]
	v_mfma_f32_16x16x32_bf16 v[50:53], v[182:185], v[190:193], v[50:53]
	v_mfma_f32_16x16x32_bf16 v[38:41], v[174:177], v[198:201], v[38:41]
	v_mfma_f32_16x16x32_bf16 v[34:37], v[182:185], v[198:201], v[34:37]
	v_mfma_f32_16x16x32_bf16 v[22:25], v[174:177], v[206:209], v[22:25]
	v_mfma_f32_16x16x32_bf16 v[18:21], v[182:185], v[206:209], v[18:21]
	v_mfma_f32_16x16x32_bf16 v[6:9], v[174:177], v[230:233], v[6:9]
	v_mfma_f32_16x16x32_bf16 v[2:5], v[182:185], v[230:233], v[2:5]
	v_mfma_f32_16x16x32_bf16 v[54:57], v[178:181], v[194:197], v[54:57]
	v_mfma_f32_16x16x32_bf16 v[50:53], v[186:189], v[194:197], v[50:53]
	v_mfma_f32_16x16x32_bf16 v[38:41], v[178:181], v[202:205], v[38:41]
	v_mfma_f32_16x16x32_bf16 v[34:37], v[186:189], v[202:205], v[34:37]
	v_mfma_f32_16x16x32_bf16 v[22:25], v[178:181], v[226:229], v[22:25]
	v_mfma_f32_16x16x32_bf16 v[18:21], v[186:189], v[226:229], v[18:21]
	v_mfma_f32_16x16x32_bf16 v[6:9], v[178:181], v[234:237], v[6:9]
	v_mfma_f32_16x16x32_bf16 v[2:5], v[186:189], v[234:237], v[2:5]
	s_setprio 0
	s_barrier
	s_add_i32 s60, 0, 0x18000
	v_add_u32_e32 v163, s60, v150
	s_add_i32 s61, 0, 0x1c000
	ds_read_b128 v[152:155], v163
	ds_read_b128 v[156:159], v163 offset:1024
	ds_read_b128 v[166:169], v163 offset:2048
	ds_read_b128 v[170:173], v163 offset:3072
	v_add_u32_e32 v163, s61, v150
	ds_read_b128 v[174:177], v163
	ds_read_b128 v[178:181], v163 offset:1024
	ds_read_b128 v[182:185], v163 offset:2048
	ds_read_b128 v[186:189], v163 offset:3072
	s_add_u32 s30, s30, 0x40000
	s_addc_u32 s31, s31, 0
	s_mov_b32 m0, s40
	v_lshl_add_u64 v[238:239], s[30:31], 0, v[130:131]
	ds_read_b128 v[190:193], v151 offset:32768
	ds_read_b128 v[194:197], v151 offset:33792
	ds_read_b128 v[198:201], v151 offset:34816
	ds_read_b128 v[202:205], v151 offset:35840
	ds_read_b128 v[206:209], v151 offset:36864
	ds_read_b128 v[226:229], v151 offset:37888
	ds_read_b128 v[230:233], v151 offset:38912
	ds_read_b128 v[234:237], v151 offset:39936
	global_load_lds_dwordx4 v[238:239], off
	v_lshl_add_u64 v[238:239], s[30:31], 0, v[134:135]
	s_mov_b32 m0, s41
	s_nop 0
	global_load_lds_dwordx4 v[238:239], off
	s_waitcnt vmcnt(8)
	s_waitcnt lgkmcnt(0)
	v_mfma_f32_16x16x32_bf16 v[122:125], v[152:155], v[190:193], v[122:125]
	v_mfma_f32_16x16x32_bf16 v[126:129], v[166:169], v[190:193], v[126:129]
	v_mfma_f32_16x16x32_bf16 v[110:113], v[152:155], v[198:201], v[110:113]
	v_mfma_f32_16x16x32_bf16 v[106:109], v[166:169], v[198:201], v[106:109]
	v_mfma_f32_16x16x32_bf16 v[94:97], v[152:155], v[206:209], v[94:97]
	v_mfma_f32_16x16x32_bf16 v[90:93], v[166:169], v[206:209], v[90:93]
	v_mfma_f32_16x16x32_bf16 v[78:81], v[152:155], v[230:233], v[78:81]
	v_mfma_f32_16x16x32_bf16 v[74:77], v[166:169], v[230:233], v[74:77]
	v_mfma_f32_16x16x32_bf16 v[122:125], v[156:159], v[194:197], v[122:125]
	v_mfma_f32_16x16x32_bf16 v[126:129], v[170:173], v[194:197], v[126:129]
	v_mfma_f32_16x16x32_bf16 v[110:113], v[156:159], v[202:205], v[110:113]
	v_mfma_f32_16x16x32_bf16 v[106:109], v[170:173], v[202:205], v[106:109]
	v_mfma_f32_16x16x32_bf16 v[94:97], v[156:159], v[226:229], v[94:97]
	v_mfma_f32_16x16x32_bf16 v[90:93], v[170:173], v[226:229], v[90:93]
	v_mfma_f32_16x16x32_bf16 v[78:81], v[156:159], v[234:237], v[78:81]
	v_mfma_f32_16x16x32_bf16 v[74:77], v[170:173], v[234:237], v[74:77]
	s_barrier
	s_setprio 1
	s_waitcnt lgkmcnt(0)
	v_mfma_f32_16x16x32_bf16 v[118:121], v[174:177], v[190:193], v[118:121]
	v_mfma_f32_16x16x32_bf16 v[114:117], v[182:185], v[190:193], v[114:117]
	v_mfma_f32_16x16x32_bf16 v[102:105], v[174:177], v[198:201], v[102:105]
	v_mfma_f32_16x16x32_bf16 v[98:101], v[182:185], v[198:201], v[98:101]
	v_mfma_f32_16x16x32_bf16 v[86:89], v[174:177], v[206:209], v[86:89]
	v_mfma_f32_16x16x32_bf16 v[82:85], v[182:185], v[206:209], v[82:85]
	v_mfma_f32_16x16x32_bf16 v[70:73], v[174:177], v[230:233], v[70:73]
	v_mfma_f32_16x16x32_bf16 v[66:69], v[182:185], v[230:233], v[66:69]
	v_mfma_f32_16x16x32_bf16 v[118:121], v[178:181], v[194:197], v[118:121]
	v_mfma_f32_16x16x32_bf16 v[114:117], v[186:189], v[194:197], v[114:117]
	v_mfma_f32_16x16x32_bf16 v[102:105], v[178:181], v[202:205], v[102:105]
	v_mfma_f32_16x16x32_bf16 v[98:101], v[186:189], v[202:205], v[98:101]
	v_mfma_f32_16x16x32_bf16 v[86:89], v[178:181], v[226:229], v[86:89]
	v_mfma_f32_16x16x32_bf16 v[82:85], v[186:189], v[226:229], v[82:85]
	v_mfma_f32_16x16x32_bf16 v[70:73], v[178:181], v[234:237], v[70:73]
	v_mfma_f32_16x16x32_bf16 v[66:69], v[186:189], v[234:237], v[66:69]
	s_setprio 0
	s_barrier
	s_add_i32 s30, s60, s37
	v_lshl_add_u64 v[160:161], v[160:161], 0, s[16:17]
	s_mov_b32 m0, s30
	ds_read_b128 v[190:193], v151 offset:49152
	ds_read_b128 v[194:197], v151 offset:50176
	ds_read_b128 v[198:201], v151 offset:51200
	ds_read_b128 v[202:205], v151 offset:52224
	ds_read_b128 v[206:209], v151 offset:53248
	ds_read_b128 v[226:229], v151 offset:54272
	ds_read_b128 v[230:233], v151 offset:55296
	ds_read_b128 v[234:237], v151 offset:56320
	global_load_lds_dwordx4 v[160:161], off
	s_add_i32 m0, s30, 0x2000
	s_add_u32 s28, s28, 0x40080
	v_lshl_add_u64 v[160:161], v[210:211], 0, s[16:17]
	s_addc_u32 s29, s29, 0
	s_add_i32 s30, s61, s37
	global_load_lds_dwordx4 v[160:161], off
	v_lshl_add_u64 v[160:161], s[28:29], 0, v[132:133]
	s_mov_b32 m0, s30
	s_nop 0
	global_load_lds_dwordx4 v[160:161], off
	v_lshl_add_u64 v[160:161], s[28:29], 0, v[136:137]
	s_add_i32 m0, s30, 0x2000
	s_nop 0
	global_load_lds_dwordx4 v[160:161], off
	v_lshl_add_u64 v[160:161], v[214:215], 0, s[16:17]
	s_mov_b32 m0, s43
	s_nop 0
	global_load_lds_dwordx4 v[160:161], off
	v_lshl_add_u64 v[160:161], v[220:221], 0, s[16:17]
	s_mov_b32 m0, s44
	s_nop 0
	global_load_lds_dwordx4 v[160:161], off
	s_waitcnt vmcnt(8)
	s_waitcnt lgkmcnt(0)
	v_mfma_f32_16x16x32_bf16 v[62:65], v[152:155], v[190:193], v[62:65]
	v_mfma_f32_16x16x32_bf16 v[58:61], v[166:169], v[190:193], v[58:61]
	v_mfma_f32_16x16x32_bf16 v[46:49], v[152:155], v[198:201], v[46:49]
	v_mfma_f32_16x16x32_bf16 v[42:45], v[166:169], v[198:201], v[42:45]
	v_mfma_f32_16x16x32_bf16 v[30:33], v[152:155], v[206:209], v[30:33]
	v_mfma_f32_16x16x32_bf16 v[26:29], v[166:169], v[206:209], v[26:29]
	v_mfma_f32_16x16x32_bf16 v[14:17], v[152:155], v[230:233], v[14:17]
	v_mfma_f32_16x16x32_bf16 v[10:13], v[166:169], v[230:233], v[10:13]
	v_mfma_f32_16x16x32_bf16 v[62:65], v[156:159], v[194:197], v[62:65]
	v_mfma_f32_16x16x32_bf16 v[58:61], v[170:173], v[194:197], v[58:61]
	v_mfma_f32_16x16x32_bf16 v[46:49], v[156:159], v[202:205], v[46:49]
	v_mfma_f32_16x16x32_bf16 v[42:45], v[170:173], v[202:205], v[42:45]
	v_mfma_f32_16x16x32_bf16 v[30:33], v[156:159], v[226:229], v[30:33]
	v_mfma_f32_16x16x32_bf16 v[26:29], v[170:173], v[226:229], v[26:29]
	v_mfma_f32_16x16x32_bf16 v[14:17], v[156:159], v[234:237], v[14:17]
	v_mfma_f32_16x16x32_bf16 v[10:13], v[170:173], v[234:237], v[10:13]
	s_barrier
	s_setprio 1
	s_waitcnt lgkmcnt(0)
	v_mfma_f32_16x16x32_bf16 v[54:57], v[174:177], v[190:193], v[54:57]
	v_mfma_f32_16x16x32_bf16 v[50:53], v[182:185], v[190:193], v[50:53]
	v_mfma_f32_16x16x32_bf16 v[38:41], v[174:177], v[198:201], v[38:41]
	v_mfma_f32_16x16x32_bf16 v[34:37], v[182:185], v[198:201], v[34:37]
	v_mfma_f32_16x16x32_bf16 v[22:25], v[174:177], v[206:209], v[22:25]
	v_mfma_f32_16x16x32_bf16 v[18:21], v[182:185], v[206:209], v[18:21]
	v_mfma_f32_16x16x32_bf16 v[6:9], v[174:177], v[230:233], v[6:9]
	v_mfma_f32_16x16x32_bf16 v[2:5], v[182:185], v[230:233], v[2:5]
	v_mfma_f32_16x16x32_bf16 v[54:57], v[178:181], v[194:197], v[54:57]
	v_mfma_f32_16x16x32_bf16 v[50:53], v[186:189], v[194:197], v[50:53]
	v_mfma_f32_16x16x32_bf16 v[38:41], v[178:181], v[202:205], v[38:41]
	v_mfma_f32_16x16x32_bf16 v[34:37], v[186:189], v[202:205], v[34:37]
	v_mfma_f32_16x16x32_bf16 v[22:25], v[178:181], v[226:229], v[22:25]
	v_mfma_f32_16x16x32_bf16 v[18:21], v[186:189], v[226:229], v[18:21]
	v_mfma_f32_16x16x32_bf16 v[6:9], v[178:181], v[234:237], v[6:9]
	v_mfma_f32_16x16x32_bf16 v[2:5], v[186:189], v[234:237], v[2:5]
	s_setprio 0
	s_barrier
	s_add_i32 s59, s59, 2
	s_add_u32 s26, s26, 0x100
	s_addc_u32 s27, s27, 0
	s_cmp_gt_u32 s59, 13
	s_cbranch_scc0 .LBB0_1612
	s_add_u32 s26, s49, 0xffffff00
	s_addc_u32 s27, s50, -1
	s_andn2_b64 vcc, exec, s[4:5]
	s_cbranch_vccnz .LBB0_1603
	v_mov_b32_e32 v2, 0
	s_mov_b32 s6, s18
	s_mov_b32 s12, s20
	s_mov_b64 s[14:15], s[24:25]
	s_mov_b32 s45, s48
	v_mov_b32_e32 v3, v2
	v_mov_b32_e32 v4, v2
	v_mov_b32_e32 v5, v2
	v_mov_b32_e32 v6, v2
	v_mov_b32_e32 v7, v2
	v_mov_b32_e32 v8, v2
	v_mov_b32_e32 v9, v2
	v_mov_b32_e32 v18, v2
	v_mov_b32_e32 v19, v2
	v_mov_b32_e32 v20, v2
	v_mov_b32_e32 v21, v2
	v_mov_b32_e32 v22, v2
	v_mov_b32_e32 v23, v2
	v_mov_b32_e32 v24, v2
	v_mov_b32_e32 v25, v2
	v_mov_b32_e32 v34, v2
	v_mov_b32_e32 v35, v2
	v_mov_b32_e32 v36, v2
	v_mov_b32_e32 v37, v2
	v_mov_b32_e32 v38, v2
	v_mov_b32_e32 v39, v2
	v_mov_b32_e32 v40, v2
	v_mov_b32_e32 v41, v2
	v_mov_b32_e32 v50, v2
	v_mov_b32_e32 v51, v2
	v_mov_b32_e32 v52, v2
	v_mov_b32_e32 v53, v2
	v_mov_b32_e32 v54, v2
	v_mov_b32_e32 v55, v2
	v_mov_b32_e32 v56, v2
	v_mov_b32_e32 v57, v2
	v_mov_b32_e32 v10, v2
	v_mov_b32_e32 v11, v2
	v_mov_b32_e32 v12, v2
	v_mov_b32_e32 v13, v2
	v_mov_b32_e32 v14, v2
	v_mov_b32_e32 v15, v2
	v_mov_b32_e32 v16, v2
	v_mov_b32_e32 v17, v2
	v_mov_b32_e32 v26, v2
	v_mov_b32_e32 v27, v2
	v_mov_b32_e32 v28, v2
	v_mov_b32_e32 v29, v2
	v_mov_b32_e32 v30, v2
	v_mov_b32_e32 v31, v2
	v_mov_b32_e32 v32, v2
	v_mov_b32_e32 v33, v2
	v_mov_b32_e32 v42, v2
	v_mov_b32_e32 v43, v2
	v_mov_b32_e32 v44, v2
	v_mov_b32_e32 v45, v2
	v_mov_b32_e32 v46, v2
	v_mov_b32_e32 v47, v2
	v_mov_b32_e32 v48, v2
	v_mov_b32_e32 v49, v2
	v_mov_b32_e32 v58, v2
	v_mov_b32_e32 v59, v2
	v_mov_b32_e32 v60, v2
	v_mov_b32_e32 v61, v2
	v_mov_b32_e32 v62, v2
	v_mov_b32_e32 v63, v2
	v_mov_b32_e32 v64, v2
	v_mov_b32_e32 v65, v2
	v_mov_b32_e32 v66, v2
	v_mov_b32_e32 v67, v2
	v_mov_b32_e32 v68, v2
	v_mov_b32_e32 v69, v2
	v_mov_b32_e32 v70, v2
	v_mov_b32_e32 v71, v2
	v_mov_b32_e32 v72, v2
	v_mov_b32_e32 v73, v2
	v_mov_b32_e32 v82, v2
	v_mov_b32_e32 v83, v2
	v_mov_b32_e32 v84, v2
	v_mov_b32_e32 v85, v2
	v_mov_b32_e32 v86, v2
	v_mov_b32_e32 v87, v2
	v_mov_b32_e32 v88, v2
	v_mov_b32_e32 v89, v2
	v_mov_b32_e32 v98, v2
	v_mov_b32_e32 v99, v2
	v_mov_b32_e32 v100, v2
	v_mov_b32_e32 v101, v2
	v_mov_b32_e32 v102, v2
	v_mov_b32_e32 v103, v2
	v_mov_b32_e32 v104, v2
	v_mov_b32_e32 v105, v2
	v_mov_b32_e32 v114, v2
	v_mov_b32_e32 v115, v2
	v_mov_b32_e32 v116, v2
	v_mov_b32_e32 v117, v2
	v_mov_b32_e32 v118, v2
	v_mov_b32_e32 v119, v2
	v_mov_b32_e32 v120, v2
	v_mov_b32_e32 v121, v2
	v_mov_b32_e32 v74, v2
	v_mov_b32_e32 v75, v2
	v_mov_b32_e32 v76, v2
	v_mov_b32_e32 v77, v2
	v_mov_b32_e32 v78, v2
	v_mov_b32_e32 v79, v2
	v_mov_b32_e32 v80, v2
	v_mov_b32_e32 v81, v2
	v_mov_b32_e32 v90, v2
	v_mov_b32_e32 v91, v2
	v_mov_b32_e32 v92, v2
	v_mov_b32_e32 v93, v2
	v_mov_b32_e32 v94, v2
	v_mov_b32_e32 v95, v2
	v_mov_b32_e32 v96, v2
	v_mov_b32_e32 v97, v2
	v_mov_b32_e32 v106, v2
	v_mov_b32_e32 v107, v2
	v_mov_b32_e32 v108, v2
	v_mov_b32_e32 v109, v2
	v_mov_b32_e32 v110, v2
	v_mov_b32_e32 v111, v2
	v_mov_b32_e32 v112, v2
	v_mov_b32_e32 v113, v2
	v_mov_b32_e32 v126, v2
	v_mov_b32_e32 v127, v2
	v_mov_b32_e32 v128, v2
	v_mov_b32_e32 v129, v2
	v_mov_b32_e32 v122, v2
	v_mov_b32_e32 v123, v2
	v_mov_b32_e32 v124, v2
	v_mov_b32_e32 v125, v2
	s_andn2_b64 vcc, exec, s[0:1]
	s_cbranch_vccnz .LBB0_1604

.LBB0_1753:
	ds_read_b128 v[146:149], v157
	ds_read_b128 v[160:163], v157 offset:1024
	ds_read_b128 v[164:167], v157 offset:2048
	ds_read_b128 v[168:171], v157 offset:3072
	ds_read_b128 v[172:175], v158
	ds_read_b128 v[176:179], v158 offset:1024
	ds_read_b128 v[180:183], v158 offset:2048
	ds_read_b128 v[184:187], v158 offset:3072
	s_add_u32 s38, s36, 0xfffc0080
	s_addc_u32 s39, s37, -1
	s_cmp_eq_u32 s65, 12
	s_cselect_b32 s41, s27, s39
	s_cselect_b32 s40, s59, s38
	s_cselect_b32 s39, s25, s64
	s_cselect_b32 s38, s60, s61
	v_lshl_add_u64 v[150:151], s[36:37], 0, v[138:139]
	s_add_i32 m0, s35, 0xc000
	ds_read_b128 v[188:191], v159
	ds_read_b128 v[192:195], v159 offset:1024
	ds_read_b128 v[196:199], v159 offset:2048
	ds_read_b128 v[200:203], v159 offset:3072
	ds_read_b128 v[204:207], v159 offset:4096
	ds_read_b128 v[208:211], v159 offset:5120
	ds_read_b128 v[218:221], v159 offset:6144
	ds_read_b128 v[226:229], v159 offset:7168
	global_load_lds_dwordx4 v[150:151], off
	v_lshl_add_u64 v[150:151], s[36:37], 0, v[140:141]
	s_add_i32 m0, s35, 0xe000
	s_nop 0
	global_load_lds_dwordx4 v[150:151], off
	s_waitcnt vmcnt(8)
	s_waitcnt lgkmcnt(0)
	v_mfma_f32_16x16x32_bf16 v[126:129], v[146:149], v[188:191], v[126:129]
	v_mfma_f32_16x16x32_bf16 v[122:125], v[164:167], v[188:191], v[122:125]
	v_mfma_f32_16x16x32_bf16 v[110:113], v[146:149], v[196:199], v[110:113]
	v_mfma_f32_16x16x32_bf16 v[106:109], v[164:167], v[196:199], v[106:109]
	v_mfma_f32_16x16x32_bf16 v[94:97], v[146:149], v[204:207], v[94:97]
	v_mfma_f32_16x16x32_bf16 v[90:93], v[164:167], v[204:207], v[90:93]
	v_mfma_f32_16x16x32_bf16 v[78:81], v[146:149], v[218:221], v[78:81]
	v_mfma_f32_16x16x32_bf16 v[74:77], v[164:167], v[218:221], v[74:77]
	v_mfma_f32_16x16x32_bf16 v[126:129], v[160:163], v[192:195], v[126:129]
	v_mfma_f32_16x16x32_bf16 v[122:125], v[168:171], v[192:195], v[122:125]
	v_mfma_f32_16x16x32_bf16 v[110:113], v[160:163], v[200:203], v[110:113]
	v_mfma_f32_16x16x32_bf16 v[106:109], v[168:171], v[200:203], v[106:109]
	v_mfma_f32_16x16x32_bf16 v[94:97], v[160:163], v[208:211], v[94:97]
	v_mfma_f32_16x16x32_bf16 v[90:93], v[168:171], v[208:211], v[90:93]
	v_mfma_f32_16x16x32_bf16 v[78:81], v[160:163], v[226:229], v[78:81]
	v_mfma_f32_16x16x32_bf16 v[74:77], v[168:171], v[226:229], v[74:77]
	s_barrier
	s_setprio 1
	s_waitcnt lgkmcnt(0)
	v_mfma_f32_16x16x32_bf16 v[118:121], v[172:175], v[188:191], v[118:121]
	v_mfma_f32_16x16x32_bf16 v[114:117], v[180:183], v[188:191], v[114:117]
	v_mfma_f32_16x16x32_bf16 v[102:105], v[172:175], v[196:199], v[102:105]
	v_mfma_f32_16x16x32_bf16 v[98:101], v[180:183], v[196:199], v[98:101]
	v_mfma_f32_16x16x32_bf16 v[86:89], v[172:175], v[204:207], v[86:89]
	v_mfma_f32_16x16x32_bf16 v[82:85], v[180:183], v[204:207], v[82:85]
	v_mfma_f32_16x16x32_bf16 v[70:73], v[172:175], v[218:221], v[70:73]
	v_mfma_f32_16x16x32_bf16 v[66:69], v[180:183], v[218:221], v[66:69]
	v_mfma_f32_16x16x32_bf16 v[118:121], v[176:179], v[192:195], v[118:121]
	v_mfma_f32_16x16x32_bf16 v[114:117], v[184:187], v[192:195], v[114:117]
	v_mfma_f32_16x16x32_bf16 v[102:105], v[176:179], v[200:203], v[102:105]
	v_mfma_f32_16x16x32_bf16 v[98:101], v[184:187], v[200:203], v[98:101]
	v_mfma_f32_16x16x32_bf16 v[86:89], v[176:179], v[208:211], v[86:89]
	v_mfma_f32_16x16x32_bf16 v[82:85], v[184:187], v[208:211], v[82:85]
	v_mfma_f32_16x16x32_bf16 v[70:73], v[176:179], v[226:229], v[70:73]
	v_mfma_f32_16x16x32_bf16 v[66:69], v[184:187], v[226:229], v[66:69]
	s_setprio 0
	s_barrier
	s_add_i32 s66, s50, s33
	v_lshl_add_u64 v[150:151], s[38:39], 0, v[132:133]
	s_mov_b32 m0, s66
	ds_read_b128 v[188:191], v159 offset:16384
	ds_read_b128 v[192:195], v159 offset:17408
	ds_read_b128 v[196:199], v159 offset:18432
	ds_read_b128 v[200:203], v159 offset:19456
	ds_read_b128 v[204:207], v159 offset:20480
	ds_read_b128 v[208:211], v159 offset:21504
	ds_read_b128 v[218:221], v159 offset:22528
	ds_read_b128 v[226:229], v159 offset:23552
	global_load_lds_dwordx4 v[150:151], off
	s_add_i32 m0, s66, 0x2000
	s_add_u32 s66, s38, 0x40000
	v_lshl_add_u64 v[214:215], s[38:39], 0, v[136:137]
	s_addc_u32 s67, s39, 0
	s_add_i32 s68, s51, s33
	global_load_lds_dwordx4 v[214:215], off
	v_lshl_add_u64 v[230:231], s[66:67], 0, v[132:133]
	s_mov_b32 m0, s68
	v_lshl_add_u64 v[232:233], s[40:41], 0, v[134:135]
	global_load_lds_dwordx4 v[230:231], off
	v_lshl_add_u64 v[230:231], s[66:67], 0, v[136:137]
	s_add_i32 m0, s68, 0x2000
	s_nop 0
	global_load_lds_dwordx4 v[230:231], off
	v_lshl_add_u64 v[230:231], s[40:41], 0, v[130:131]
	s_mov_b32 m0, s35
	s_nop 0
	global_load_lds_dwordx4 v[230:231], off
	s_mov_b32 m0, s42
	s_nop 0
	global_load_lds_dwordx4 v[232:233], off
	s_waitcnt vmcnt(8)
	s_waitcnt lgkmcnt(0)
	v_mfma_f32_16x16x32_bf16 v[62:65], v[146:149], v[188:191], v[62:65]
	v_mfma_f32_16x16x32_bf16 v[58:61], v[164:167], v[188:191], v[58:61]
	v_mfma_f32_16x16x32_bf16 v[46:49], v[146:149], v[196:199], v[46:49]
	v_mfma_f32_16x16x32_bf16 v[42:45], v[164:167], v[196:199], v[42:45]
	v_mfma_f32_16x16x32_bf16 v[30:33], v[146:149], v[204:207], v[30:33]
	v_mfma_f32_16x16x32_bf16 v[26:29], v[164:167], v[204:207], v[26:29]
	v_mfma_f32_16x16x32_bf16 v[14:17], v[146:149], v[218:221], v[14:17]
	v_mfma_f32_16x16x32_bf16 v[10:13], v[164:167], v[218:221], v[10:13]
	v_mfma_f32_16x16x32_bf16 v[62:65], v[160:163], v[192:195], v[62:65]
	v_mfma_f32_16x16x32_bf16 v[58:61], v[168:171], v[192:195], v[58:61]
	v_mfma_f32_16x16x32_bf16 v[46:49], v[160:163], v[200:203], v[46:49]
	v_mfma_f32_16x16x32_bf16 v[42:45], v[168:171], v[200:203], v[42:45]
	v_mfma_f32_16x16x32_bf16 v[30:33], v[160:163], v[208:211], v[30:33]
	v_mfma_f32_16x16x32_bf16 v[26:29], v[168:171], v[208:211], v[26:29]
	v_mfma_f32_16x16x32_bf16 v[14:17], v[160:163], v[226:229], v[14:17]
	v_mfma_f32_16x16x32_bf16 v[10:13], v[168:171], v[226:229], v[10:13]
	s_barrier
	s_setprio 1
	s_waitcnt lgkmcnt(0)
	v_mfma_f32_16x16x32_bf16 v[54:57], v[172:175], v[188:191], v[54:57]
	v_mfma_f32_16x16x32_bf16 v[50:53], v[180:183], v[188:191], v[50:53]
	v_mfma_f32_16x16x32_bf16 v[38:41], v[172:175], v[196:199], v[38:41]
	v_mfma_f32_16x16x32_bf16 v[34:37], v[180:183], v[196:199], v[34:37]
	v_mfma_f32_16x16x32_bf16 v[22:25], v[172:175], v[204:207], v[22:25]
	v_mfma_f32_16x16x32_bf16 v[18:21], v[180:183], v[204:207], v[18:21]
	v_mfma_f32_16x16x32_bf16 v[6:9], v[172:175], v[218:221], v[6:9]
	v_mfma_f32_16x16x32_bf16 v[2:5], v[180:183], v[218:221], v[2:5]
	v_mfma_f32_16x16x32_bf16 v[54:57], v[176:179], v[192:195], v[54:57]
	v_mfma_f32_16x16x32_bf16 v[50:53], v[184:187], v[192:195], v[50:53]
	v_mfma_f32_16x16x32_bf16 v[38:41], v[176:179], v[200:203], v[38:41]
	v_mfma_f32_16x16x32_bf16 v[34:37], v[184:187], v[200:203], v[34:37]
	v_mfma_f32_16x16x32_bf16 v[22:25], v[176:179], v[208:211], v[22:25]
	v_mfma_f32_16x16x32_bf16 v[18:21], v[184:187], v[208:211], v[18:21]
	v_mfma_f32_16x16x32_bf16 v[6:9], v[176:179], v[226:229], v[6:9]
	v_mfma_f32_16x16x32_bf16 v[2:5], v[184:187], v[226:229], v[2:5]
	s_setprio 0
	s_barrier
	s_add_i32 s66, 0, 0x18000
	s_add_i32 s67, 0, 0x1c000
	v_add_u32_e32 v168, s66, v153
	v_add_u32_e32 v184, s67, v153
	ds_read_b128 v[146:149], v168
	ds_read_b128 v[160:163], v168 offset:1024
	ds_read_b128 v[164:167], v168 offset:2048
	ds_read_b128 v[168:171], v168 offset:3072
	ds_read_b128 v[172:175], v184
	ds_read_b128 v[176:179], v184 offset:1024
	ds_read_b128 v[180:183], v184 offset:2048
	ds_read_b128 v[184:187], v184 offset:3072
	s_add_u32 s40, s40, 0x40000
	s_addc_u32 s41, s41, 0
	s_mov_b32 m0, s43
	v_lshl_add_u64 v[234:235], s[40:41], 0, v[130:131]
	ds_read_b128 v[188:191], v159 offset:32768
	ds_read_b128 v[192:195], v159 offset:33792
	ds_read_b128 v[196:199], v159 offset:34816
	ds_read_b128 v[200:203], v159 offset:35840
	ds_read_b128 v[204:207], v159 offset:36864
	ds_read_b128 v[208:211], v159 offset:37888
	ds_read_b128 v[218:221], v159 offset:38912
	ds_read_b128 v[226:229], v159 offset:39936
	global_load_lds_dwordx4 v[234:235], off
	v_lshl_add_u64 v[234:235], s[40:41], 0, v[134:135]
	s_mov_b32 m0, s44
	s_nop 0
	global_load_lds_dwordx4 v[234:235], off
	s_waitcnt vmcnt(8)
	s_waitcnt lgkmcnt(0)
	v_mfma_f32_16x16x32_bf16 v[126:129], v[146:149], v[188:191], v[126:129]
	v_mfma_f32_16x16x32_bf16 v[122:125], v[164:167], v[188:191], v[122:125]
	v_mfma_f32_16x16x32_bf16 v[110:113], v[146:149], v[196:199], v[110:113]
	v_mfma_f32_16x16x32_bf16 v[106:109], v[164:167], v[196:199], v[106:109]
	v_mfma_f32_16x16x32_bf16 v[94:97], v[146:149], v[204:207], v[94:97]
	v_mfma_f32_16x16x32_bf16 v[90:93], v[164:167], v[204:207], v[90:93]
	v_mfma_f32_16x16x32_bf16 v[78:81], v[146:149], v[218:221], v[78:81]
	v_mfma_f32_16x16x32_bf16 v[74:77], v[164:167], v[218:221], v[74:77]
	v_mfma_f32_16x16x32_bf16 v[126:129], v[160:163], v[192:195], v[126:129]
	v_mfma_f32_16x16x32_bf16 v[122:125], v[168:171], v[192:195], v[122:125]
	v_mfma_f32_16x16x32_bf16 v[110:113], v[160:163], v[200:203], v[110:113]
	v_mfma_f32_16x16x32_bf16 v[106:109], v[168:171], v[200:203], v[106:109]
	v_mfma_f32_16x16x32_bf16 v[94:97], v[160:163], v[208:211], v[94:97]
	v_mfma_f32_16x16x32_bf16 v[90:93], v[168:171], v[208:211], v[90:93]
	v_mfma_f32_16x16x32_bf16 v[78:81], v[160:163], v[226:229], v[78:81]
	v_mfma_f32_16x16x32_bf16 v[74:77], v[168:171], v[226:229], v[74:77]
	s_barrier
	s_setprio 1
	s_waitcnt lgkmcnt(0)
	v_mfma_f32_16x16x32_bf16 v[118:121], v[172:175], v[188:191], v[118:121]
	v_mfma_f32_16x16x32_bf16 v[114:117], v[180:183], v[188:191], v[114:117]
	v_mfma_f32_16x16x32_bf16 v[102:105], v[172:175], v[196:199], v[102:105]
	v_mfma_f32_16x16x32_bf16 v[98:101], v[180:183], v[196:199], v[98:101]
	v_mfma_f32_16x16x32_bf16 v[86:89], v[172:175], v[204:207], v[86:89]
	v_mfma_f32_16x16x32_bf16 v[82:85], v[180:183], v[204:207], v[82:85]
	v_mfma_f32_16x16x32_bf16 v[70:73], v[172:175], v[218:221], v[70:73]
	v_mfma_f32_16x16x32_bf16 v[66:69], v[180:183], v[218:221], v[66:69]
	v_mfma_f32_16x16x32_bf16 v[118:121], v[176:179], v[192:195], v[118:121]
	v_mfma_f32_16x16x32_bf16 v[114:117], v[184:187], v[192:195], v[114:117]
	v_mfma_f32_16x16x32_bf16 v[102:105], v[176:179], v[200:203], v[102:105]
	v_mfma_f32_16x16x32_bf16 v[98:101], v[184:187], v[200:203], v[98:101]
	v_mfma_f32_16x16x32_bf16 v[86:89], v[176:179], v[208:211], v[86:89]
	v_mfma_f32_16x16x32_bf16 v[82:85], v[184:187], v[208:211], v[82:85]
	v_mfma_f32_16x16x32_bf16 v[70:73], v[176:179], v[226:229], v[70:73]
	v_mfma_f32_16x16x32_bf16 v[66:69], v[184:187], v[226:229], v[66:69]
	s_setprio 0
	s_barrier
	s_add_i32 s40, s66, s33
	v_lshl_add_u64 v[150:151], v[150:151], 0, s[12:13]
	s_mov_b32 m0, s40
	ds_read_b128 v[188:191], v159 offset:49152
	ds_read_b128 v[192:195], v159 offset:50176
	ds_read_b128 v[196:199], v159 offset:51200
	ds_read_b128 v[200:203], v159 offset:52224
	ds_read_b128 v[204:207], v159 offset:53248
	ds_read_b128 v[208:211], v159 offset:54272
	ds_read_b128 v[218:221], v159 offset:55296
	ds_read_b128 v[226:229], v159 offset:56320
	global_load_lds_dwordx4 v[150:151], off
	s_add_i32 m0, s40, 0x2000
	s_add_u32 s38, s38, 0x40080
	v_lshl_add_u64 v[150:151], v[214:215], 0, s[12:13]
	s_addc_u32 s39, s39, 0
	s_add_i32 s40, s67, s33
	global_load_lds_dwordx4 v[150:151], off
	v_lshl_add_u64 v[150:151], s[38:39], 0, v[132:133]
	s_mov_b32 m0, s40
	s_nop 0
	global_load_lds_dwordx4 v[150:151], off
	v_lshl_add_u64 v[150:151], s[38:39], 0, v[136:137]
	s_add_i32 m0, s40, 0x2000
	s_nop 0
	global_load_lds_dwordx4 v[150:151], off
	v_lshl_add_u64 v[150:151], v[230:231], 0, s[12:13]
	s_mov_b32 m0, s46
	s_nop 0
	global_load_lds_dwordx4 v[150:151], off
	v_lshl_add_u64 v[150:151], v[232:233], 0, s[12:13]
	s_mov_b32 m0, s47
	s_nop 0
	global_load_lds_dwordx4 v[150:151], off
	s_waitcnt vmcnt(8)
	s_waitcnt lgkmcnt(0)
	v_mfma_f32_16x16x32_bf16 v[62:65], v[146:149], v[188:191], v[62:65]
	v_mfma_f32_16x16x32_bf16 v[58:61], v[164:167], v[188:191], v[58:61]
	v_mfma_f32_16x16x32_bf16 v[46:49], v[146:149], v[196:199], v[46:49]
	v_mfma_f32_16x16x32_bf16 v[42:45], v[164:167], v[196:199], v[42:45]
	v_mfma_f32_16x16x32_bf16 v[30:33], v[146:149], v[204:207], v[30:33]
	v_mfma_f32_16x16x32_bf16 v[26:29], v[164:167], v[204:207], v[26:29]
	v_mfma_f32_16x16x32_bf16 v[14:17], v[146:149], v[218:221], v[14:17]
	v_mfma_f32_16x16x32_bf16 v[10:13], v[164:167], v[218:221], v[10:13]
	v_mfma_f32_16x16x32_bf16 v[62:65], v[160:163], v[192:195], v[62:65]
	v_mfma_f32_16x16x32_bf16 v[58:61], v[168:171], v[192:195], v[58:61]
	v_mfma_f32_16x16x32_bf16 v[46:49], v[160:163], v[200:203], v[46:49]
	v_mfma_f32_16x16x32_bf16 v[42:45], v[168:171], v[200:203], v[42:45]
	v_mfma_f32_16x16x32_bf16 v[30:33], v[160:163], v[208:211], v[30:33]
	v_mfma_f32_16x16x32_bf16 v[26:29], v[168:171], v[208:211], v[26:29]
	v_mfma_f32_16x16x32_bf16 v[14:17], v[160:163], v[226:229], v[14:17]
	v_mfma_f32_16x16x32_bf16 v[10:13], v[168:171], v[226:229], v[10:13]
	s_barrier
	s_setprio 1
	s_waitcnt lgkmcnt(0)
	v_mfma_f32_16x16x32_bf16 v[54:57], v[172:175], v[188:191], v[54:57]
	v_mfma_f32_16x16x32_bf16 v[50:53], v[180:183], v[188:191], v[50:53]
	v_mfma_f32_16x16x32_bf16 v[38:41], v[172:175], v[196:199], v[38:41]
	v_mfma_f32_16x16x32_bf16 v[34:37], v[180:183], v[196:199], v[34:37]
	v_mfma_f32_16x16x32_bf16 v[22:25], v[172:175], v[204:207], v[22:25]
	v_mfma_f32_16x16x32_bf16 v[18:21], v[180:183], v[204:207], v[18:21]
	v_mfma_f32_16x16x32_bf16 v[6:9], v[172:175], v[218:221], v[6:9]
	v_mfma_f32_16x16x32_bf16 v[2:5], v[180:183], v[218:221], v[2:5]
	v_mfma_f32_16x16x32_bf16 v[54:57], v[176:179], v[192:195], v[54:57]
	v_mfma_f32_16x16x32_bf16 v[50:53], v[184:187], v[192:195], v[50:53]
	v_mfma_f32_16x16x32_bf16 v[38:41], v[176:179], v[200:203], v[38:41]
	v_mfma_f32_16x16x32_bf16 v[34:37], v[184:187], v[200:203], v[34:37]
	v_mfma_f32_16x16x32_bf16 v[22:25], v[176:179], v[208:211], v[22:25]
	v_mfma_f32_16x16x32_bf16 v[18:21], v[184:187], v[208:211], v[18:21]
	v_mfma_f32_16x16x32_bf16 v[6:9], v[176:179], v[226:229], v[6:9]
	v_mfma_f32_16x16x32_bf16 v[2:5], v[184:187], v[226:229], v[2:5]
	s_setprio 0
	s_barrier
	s_add_i32 s65, s65, 2
	s_add_u32 s36, s36, 0x100
	s_addc_u32 s37, s37, 0
	s_add_u32 s61, s61, 0x100
	s_addc_u32 s64, s64, 0
	s_cmp_gt_u32 s65, 13
	s_cbranch_scc0 .LBB0_1753
	s_and_b64 vcc, exec, s[14:15]
	s_cbranch_vccz .LBB0_1756
	s_barrier

.LBB0_1864:
	v_add_u32_e32 v131, s47, v151
	ds_read_b128 v[154:157], v131
	ds_read_b128 v[158:161], v131 offset:1024
	ds_read_b128 v[162:165], v131 offset:2048
	ds_read_b128 v[166:169], v131 offset:3072
	v_add_u32_e32 v131, s48, v151
	ds_read_b128 v[170:173], v131
	ds_read_b128 v[174:177], v131 offset:1024
	ds_read_b128 v[178:181], v131 offset:2048
	ds_read_b128 v[182:185], v131 offset:3072
	s_add_i32 s55, s28, 2
	s_add_u32 s58, s26, 0x80
	s_addc_u32 s29, s27, 0
	s_cmp_eq_u32 s46, s28
	s_cselect_b32 s28, s6, s58
	s_cselect_b32 s29, s7, s29
	s_cselect_b32 s59, s25, s54
	s_cselect_b32 s58, s24, s53
	v_lshl_add_u64 v[132:133], s[26:27], 0, v[142:143]
	s_add_i32 m0, s38, 0xc000
	ds_read_b128 v[186:189], v152
	ds_read_b128 v[194:197], v152 offset:1024
	ds_read_b128 v[198:201], v152 offset:2048
	ds_read_b128 v[202:205], v152 offset:3072
	ds_read_b128 v[206:209], v152 offset:4096
	ds_read_b128 v[218:221], v152 offset:5120
	ds_read_b128 v[226:229], v152 offset:6144
	ds_read_b128 v[230:233], v152 offset:7168
	global_load_lds_dwordx4 v[132:133], off
	v_lshl_add_u64 v[132:133], s[26:27], 0, v[144:145]
	s_add_i32 m0, s38, 0xe000
	s_nop 0
	global_load_lds_dwordx4 v[132:133], off
	s_waitcnt vmcnt(8)
	s_waitcnt lgkmcnt(0)
	v_mfma_f32_16x16x32_bf16 v[122:125], v[154:157], v[186:189], v[122:125]
	v_mfma_f32_16x16x32_bf16 v[126:129], v[162:165], v[186:189], v[126:129]
	v_mfma_f32_16x16x32_bf16 v[114:117], v[154:157], v[198:201], v[114:117]
	v_mfma_f32_16x16x32_bf16 v[118:121], v[162:165], v[198:201], v[118:121]
	v_mfma_f32_16x16x32_bf16 v[94:97], v[154:157], v[206:209], v[94:97]
	v_mfma_f32_16x16x32_bf16 v[90:93], v[162:165], v[206:209], v[90:93]
	v_mfma_f32_16x16x32_bf16 v[78:81], v[154:157], v[226:229], v[78:81]
	v_mfma_f32_16x16x32_bf16 v[74:77], v[162:165], v[226:229], v[74:77]
	v_mfma_f32_16x16x32_bf16 v[122:125], v[158:161], v[194:197], v[122:125]
	v_mfma_f32_16x16x32_bf16 v[126:129], v[166:169], v[194:197], v[126:129]
	v_mfma_f32_16x16x32_bf16 v[114:117], v[158:161], v[202:205], v[114:117]
	v_mfma_f32_16x16x32_bf16 v[118:121], v[166:169], v[202:205], v[118:121]
	v_mfma_f32_16x16x32_bf16 v[94:97], v[158:161], v[218:221], v[94:97]
	v_mfma_f32_16x16x32_bf16 v[90:93], v[166:169], v[218:221], v[90:93]
	v_mfma_f32_16x16x32_bf16 v[78:81], v[158:161], v[230:233], v[78:81]
	v_mfma_f32_16x16x32_bf16 v[74:77], v[166:169], v[230:233], v[74:77]
	s_barrier
	s_setprio 1
	s_waitcnt lgkmcnt(0)
	v_mfma_f32_16x16x32_bf16 v[110:113], v[170:173], v[186:189], v[110:113]
	v_mfma_f32_16x16x32_bf16 v[106:109], v[178:181], v[186:189], v[106:109]
	v_mfma_f32_16x16x32_bf16 v[102:105], v[170:173], v[198:201], v[102:105]
	v_mfma_f32_16x16x32_bf16 v[98:101], v[178:181], v[198:201], v[98:101]
	v_mfma_f32_16x16x32_bf16 v[86:89], v[170:173], v[206:209], v[86:89]
	v_mfma_f32_16x16x32_bf16 v[82:85], v[178:181], v[206:209], v[82:85]
	v_mfma_f32_16x16x32_bf16 v[70:73], v[170:173], v[226:229], v[70:73]
	v_mfma_f32_16x16x32_bf16 v[66:69], v[178:181], v[226:229], v[66:69]
	v_mfma_f32_16x16x32_bf16 v[110:113], v[174:177], v[194:197], v[110:113]
	v_mfma_f32_16x16x32_bf16 v[106:109], v[182:185], v[194:197], v[106:109]
	v_mfma_f32_16x16x32_bf16 v[102:105], v[174:177], v[202:205], v[102:105]
	v_mfma_f32_16x16x32_bf16 v[98:101], v[182:185], v[202:205], v[98:101]
	v_mfma_f32_16x16x32_bf16 v[86:89], v[174:177], v[218:221], v[86:89]
	v_mfma_f32_16x16x32_bf16 v[82:85], v[182:185], v[218:221], v[82:85]
	v_mfma_f32_16x16x32_bf16 v[70:73], v[174:177], v[230:233], v[70:73]
	v_mfma_f32_16x16x32_bf16 v[66:69], v[182:185], v[230:233], v[66:69]
	s_setprio 0
	s_barrier
	s_add_i32 s60, s47, s34
	v_lshl_add_u64 v[132:133], s[58:59], 0, v[136:137]
	s_mov_b32 m0, s60
	ds_read_b128 v[186:189], v152 offset:16384
	ds_read_b128 v[194:197], v152 offset:17408
	ds_read_b128 v[198:201], v152 offset:18432
	ds_read_b128 v[202:205], v152 offset:19456
	ds_read_b128 v[206:209], v152 offset:20480
	ds_read_b128 v[218:221], v152 offset:21504
	ds_read_b128 v[226:229], v152 offset:22528
	ds_read_b128 v[230:233], v152 offset:23552
	global_load_lds_dwordx4 v[132:133], off
	s_add_i32 m0, s60, 0x2000
	v_lshl_add_u64 v[190:191], s[58:59], 0, v[140:141]
	s_add_u32 s58, s58, s12
	s_addc_u32 s59, s59, s13
	s_add_i32 s60, s48, s34
	global_load_lds_dwordx4 v[190:191], off
	v_lshl_add_u64 v[210:211], s[58:59], 0, v[136:137]
	s_mov_b32 m0, s60
	v_lshl_add_u64 v[234:235], s[58:59], 0, v[140:141]
	global_load_lds_dwordx4 v[210:211], off
	s_add_i32 m0, s60, 0x2000
	v_lshl_add_u64 v[236:237], s[28:29], 0, v[134:135]
	global_load_lds_dwordx4 v[234:235], off
	s_mov_b32 m0, s38
	v_lshl_add_u64 v[238:239], s[28:29], 0, v[138:139]
	global_load_lds_dwordx4 v[236:237], off
	s_mov_b32 m0, s39
	s_nop 0
	global_load_lds_dwordx4 v[238:239], off
	s_waitcnt vmcnt(8)
	s_waitcnt lgkmcnt(0)
	v_mfma_f32_16x16x32_bf16 v[62:65], v[154:157], v[186:189], v[62:65]
	v_mfma_f32_16x16x32_bf16 v[58:61], v[162:165], v[186:189], v[58:61]
	v_mfma_f32_16x16x32_bf16 v[46:49], v[154:157], v[198:201], v[46:49]
	v_mfma_f32_16x16x32_bf16 v[42:45], v[162:165], v[198:201], v[42:45]
	v_mfma_f32_16x16x32_bf16 v[30:33], v[154:157], v[206:209], v[30:33]
	v_mfma_f32_16x16x32_bf16 v[26:29], v[162:165], v[206:209], v[26:29]
	v_mfma_f32_16x16x32_bf16 v[14:17], v[154:157], v[226:229], v[14:17]
	v_mfma_f32_16x16x32_bf16 v[10:13], v[162:165], v[226:229], v[10:13]
	v_mfma_f32_16x16x32_bf16 v[62:65], v[158:161], v[194:197], v[62:65]
	v_mfma_f32_16x16x32_bf16 v[58:61], v[166:169], v[194:197], v[58:61]
	v_mfma_f32_16x16x32_bf16 v[46:49], v[158:161], v[202:205], v[46:49]
	v_mfma_f32_16x16x32_bf16 v[42:45], v[166:169], v[202:205], v[42:45]
	v_mfma_f32_16x16x32_bf16 v[30:33], v[158:161], v[218:221], v[30:33]
	v_mfma_f32_16x16x32_bf16 v[26:29], v[166:169], v[218:221], v[26:29]
	v_mfma_f32_16x16x32_bf16 v[14:17], v[158:161], v[230:233], v[14:17]
	v_mfma_f32_16x16x32_bf16 v[10:13], v[166:169], v[230:233], v[10:13]
	s_barrier
	s_setprio 1
	s_waitcnt lgkmcnt(0)
	v_mfma_f32_16x16x32_bf16 v[54:57], v[170:173], v[186:189], v[54:57]
	v_mfma_f32_16x16x32_bf16 v[50:53], v[178:181], v[186:189], v[50:53]
	v_mfma_f32_16x16x32_bf16 v[38:41], v[170:173], v[198:201], v[38:41]
	v_mfma_f32_16x16x32_bf16 v[34:37], v[178:181], v[198:201], v[34:37]
	v_mfma_f32_16x16x32_bf16 v[22:25], v[170:173], v[206:209], v[22:25]
	v_mfma_f32_16x16x32_bf16 v[18:21], v[178:181], v[206:209], v[18:21]
	v_mfma_f32_16x16x32_bf16 v[6:9], v[170:173], v[226:229], v[6:9]
	v_mfma_f32_16x16x32_bf16 v[2:5], v[178:181], v[226:229], v[2:5]
	v_mfma_f32_16x16x32_bf16 v[54:57], v[174:177], v[194:197], v[54:57]
	v_mfma_f32_16x16x32_bf16 v[50:53], v[182:185], v[194:197], v[50:53]
	v_mfma_f32_16x16x32_bf16 v[38:41], v[174:177], v[202:205], v[38:41]
	v_mfma_f32_16x16x32_bf16 v[34:37], v[182:185], v[202:205], v[34:37]
	v_mfma_f32_16x16x32_bf16 v[22:25], v[174:177], v[218:221], v[22:25]
	v_mfma_f32_16x16x32_bf16 v[18:21], v[182:185], v[218:221], v[18:21]
	v_mfma_f32_16x16x32_bf16 v[6:9], v[174:177], v[230:233], v[6:9]
	v_mfma_f32_16x16x32_bf16 v[2:5], v[182:185], v[230:233], v[2:5]
	s_setprio 0
	s_barrier
	s_add_i32 s58, 0, 0x18000
	v_add_u32_e32 v131, s58, v151
	s_add_i32 s59, 0, 0x1c000
	ds_read_b128 v[154:157], v131
	ds_read_b128 v[158:161], v131 offset:1024
	ds_read_b128 v[162:165], v131 offset:2048
	ds_read_b128 v[166:169], v131 offset:3072
	v_add_u32_e32 v131, s59, v151
	ds_read_b128 v[170:173], v131
	ds_read_b128 v[174:177], v131 offset:1024
	ds_read_b128 v[178:181], v131 offset:2048
	ds_read_b128 v[182:185], v131 offset:3072
	s_add_u32 s28, s28, s12
	s_addc_u32 s29, s29, s13
	s_mov_b32 m0, s40
	v_lshl_add_u64 v[240:241], s[28:29], 0, v[134:135]
	ds_read_b128 v[186:189], v152 offset:32768
	ds_read_b128 v[194:197], v152 offset:33792
	ds_read_b128 v[198:201], v152 offset:34816
	ds_read_b128 v[202:205], v152 offset:35840
	ds_read_b128 v[206:209], v152 offset:36864
	ds_read_b128 v[218:221], v152 offset:37888
	ds_read_b128 v[226:229], v152 offset:38912
	ds_read_b128 v[230:233], v152 offset:39936
	global_load_lds_dwordx4 v[240:241], off
	v_lshl_add_u64 v[240:241], s[28:29], 0, v[138:139]
	s_mov_b32 m0, s41
	s_nop 0
	global_load_lds_dwordx4 v[240:241], off
	s_waitcnt vmcnt(8)
	s_waitcnt lgkmcnt(0)
	v_mfma_f32_16x16x32_bf16 v[122:125], v[154:157], v[186:189], v[122:125]
	v_mfma_f32_16x16x32_bf16 v[126:129], v[162:165], v[186:189], v[126:129]
	v_mfma_f32_16x16x32_bf16 v[114:117], v[154:157], v[198:201], v[114:117]
	v_mfma_f32_16x16x32_bf16 v[118:121], v[162:165], v[198:201], v[118:121]
	v_mfma_f32_16x16x32_bf16 v[94:97], v[154:157], v[206:209], v[94:97]
	v_mfma_f32_16x16x32_bf16 v[90:93], v[162:165], v[206:209], v[90:93]
	v_mfma_f32_16x16x32_bf16 v[78:81], v[154:157], v[226:229], v[78:81]
	v_mfma_f32_16x16x32_bf16 v[74:77], v[162:165], v[226:229], v[74:77]
	v_mfma_f32_16x16x32_bf16 v[122:125], v[158:161], v[194:197], v[122:125]
	v_mfma_f32_16x16x32_bf16 v[126:129], v[166:169], v[194:197], v[126:129]
	v_mfma_f32_16x16x32_bf16 v[114:117], v[158:161], v[202:205], v[114:117]
	v_mfma_f32_16x16x32_bf16 v[118:121], v[166:169], v[202:205], v[118:121]
	v_mfma_f32_16x16x32_bf16 v[94:97], v[158:161], v[218:221], v[94:97]
	v_mfma_f32_16x16x32_bf16 v[90:93], v[166:169], v[218:221], v[90:93]
	v_mfma_f32_16x16x32_bf16 v[78:81], v[158:161], v[230:233], v[78:81]
	v_mfma_f32_16x16x32_bf16 v[74:77], v[166:169], v[230:233], v[74:77]
	s_barrier
	s_setprio 1
	s_waitcnt lgkmcnt(0)
	v_mfma_f32_16x16x32_bf16 v[110:113], v[170:173], v[186:189], v[110:113]
	v_mfma_f32_16x16x32_bf16 v[106:109], v[178:181], v[186:189], v[106:109]
	v_mfma_f32_16x16x32_bf16 v[102:105], v[170:173], v[198:201], v[102:105]
	v_mfma_f32_16x16x32_bf16 v[98:101], v[178:181], v[198:201], v[98:101]
	v_mfma_f32_16x16x32_bf16 v[86:89], v[170:173], v[206:209], v[86:89]
	v_mfma_f32_16x16x32_bf16 v[82:85], v[178:181], v[206:209], v[82:85]
	v_mfma_f32_16x16x32_bf16 v[70:73], v[170:173], v[226:229], v[70:73]
	v_mfma_f32_16x16x32_bf16 v[66:69], v[178:181], v[226:229], v[66:69]
	v_mfma_f32_16x16x32_bf16 v[110:113], v[174:177], v[194:197], v[110:113]
	v_mfma_f32_16x16x32_bf16 v[106:109], v[182:185], v[194:197], v[106:109]
	v_mfma_f32_16x16x32_bf16 v[102:105], v[174:177], v[202:205], v[102:105]
	v_mfma_f32_16x16x32_bf16 v[98:101], v[182:185], v[202:205], v[98:101]
	v_mfma_f32_16x16x32_bf16 v[86:89], v[174:177], v[218:221], v[86:89]
	v_mfma_f32_16x16x32_bf16 v[82:85], v[182:185], v[218:221], v[82:85]
	v_mfma_f32_16x16x32_bf16 v[70:73], v[174:177], v[230:233], v[70:73]
	v_mfma_f32_16x16x32_bf16 v[66:69], v[182:185], v[230:233], v[66:69]
	s_setprio 0
	s_barrier
	s_add_i32 s28, s58, s34
	v_lshl_add_u64 v[132:133], v[132:133], 0, s[20:21]
	s_mov_b32 m0, s28
	ds_read_b128 v[186:189], v152 offset:49152
	ds_read_b128 v[194:197], v152 offset:50176
	ds_read_b128 v[198:201], v152 offset:51200
	ds_read_b128 v[202:205], v152 offset:52224
	ds_read_b128 v[206:209], v152 offset:53248
	ds_read_b128 v[218:221], v152 offset:54272
	ds_read_b128 v[226:229], v152 offset:55296
	ds_read_b128 v[230:233], v152 offset:56320
	global_load_lds_dwordx4 v[132:133], off
	v_lshl_add_u64 v[132:133], v[190:191], 0, s[20:21]
	s_add_i32 m0, s28, 0x2000
	s_add_i32 s28, s59, s34
	global_load_lds_dwordx4 v[132:133], off
	v_lshl_add_u64 v[132:133], v[210:211], 0, s[20:21]
	s_mov_b32 m0, s28
	s_nop 0
	global_load_lds_dwordx4 v[132:133], off
	v_lshl_add_u64 v[132:133], v[234:235], 0, s[20:21]
	s_add_i32 m0, s28, 0x2000
	s_nop 0
	global_load_lds_dwordx4 v[132:133], off
	v_lshl_add_u64 v[132:133], v[236:237], 0, s[20:21]
	s_mov_b32 m0, s42
	s_nop 0
	global_load_lds_dwordx4 v[132:133], off
	v_lshl_add_u64 v[132:133], v[238:239], 0, s[20:21]
	s_mov_b32 m0, s43
	s_nop 0
	global_load_lds_dwordx4 v[132:133], off
	s_waitcnt vmcnt(8)
	s_waitcnt lgkmcnt(0)
	v_mfma_f32_16x16x32_bf16 v[62:65], v[154:157], v[186:189], v[62:65]
	v_mfma_f32_16x16x32_bf16 v[58:61], v[162:165], v[186:189], v[58:61]
	v_mfma_f32_16x16x32_bf16 v[46:49], v[154:157], v[198:201], v[46:49]
	v_mfma_f32_16x16x32_bf16 v[42:45], v[162:165], v[198:201], v[42:45]
	v_mfma_f32_16x16x32_bf16 v[30:33], v[154:157], v[206:209], v[30:33]
	v_mfma_f32_16x16x32_bf16 v[26:29], v[162:165], v[206:209], v[26:29]
	v_mfma_f32_16x16x32_bf16 v[14:17], v[154:157], v[226:229], v[14:17]
	v_mfma_f32_16x16x32_bf16 v[10:13], v[162:165], v[226:229], v[10:13]
	v_mfma_f32_16x16x32_bf16 v[62:65], v[158:161], v[194:197], v[62:65]
	v_mfma_f32_16x16x32_bf16 v[58:61], v[166:169], v[194:197], v[58:61]
	v_mfma_f32_16x16x32_bf16 v[46:49], v[158:161], v[202:205], v[46:49]
	v_mfma_f32_16x16x32_bf16 v[42:45], v[166:169], v[202:205], v[42:45]
	v_mfma_f32_16x16x32_bf16 v[30:33], v[158:161], v[218:221], v[30:33]
	v_mfma_f32_16x16x32_bf16 v[26:29], v[166:169], v[218:221], v[26:29]
	v_mfma_f32_16x16x32_bf16 v[14:17], v[158:161], v[230:233], v[14:17]
	v_mfma_f32_16x16x32_bf16 v[10:13], v[166:169], v[230:233], v[10:13]
	s_barrier
	s_setprio 1
	s_waitcnt lgkmcnt(0)
	v_mfma_f32_16x16x32_bf16 v[54:57], v[170:173], v[186:189], v[54:57]
	v_mfma_f32_16x16x32_bf16 v[50:53], v[178:181], v[186:189], v[50:53]
	v_mfma_f32_16x16x32_bf16 v[38:41], v[170:173], v[198:201], v[38:41]
	v_mfma_f32_16x16x32_bf16 v[34:37], v[178:181], v[198:201], v[34:37]
	v_mfma_f32_16x16x32_bf16 v[22:25], v[170:173], v[206:209], v[22:25]
	v_mfma_f32_16x16x32_bf16 v[18:21], v[178:181], v[206:209], v[18:21]
	v_mfma_f32_16x16x32_bf16 v[6:9], v[170:173], v[226:229], v[6:9]
	v_mfma_f32_16x16x32_bf16 v[2:5], v[178:181], v[226:229], v[2:5]
	v_mfma_f32_16x16x32_bf16 v[54:57], v[174:177], v[194:197], v[54:57]
	v_mfma_f32_16x16x32_bf16 v[50:53], v[182:185], v[194:197], v[50:53]
	v_mfma_f32_16x16x32_bf16 v[38:41], v[174:177], v[202:205], v[38:41]
	v_mfma_f32_16x16x32_bf16 v[34:37], v[182:185], v[202:205], v[34:37]
	v_mfma_f32_16x16x32_bf16 v[22:25], v[174:177], v[218:221], v[22:25]
	v_mfma_f32_16x16x32_bf16 v[18:21], v[182:185], v[218:221], v[18:21]
	v_mfma_f32_16x16x32_bf16 v[6:9], v[174:177], v[230:233], v[6:9]
	v_mfma_f32_16x16x32_bf16 v[2:5], v[182:185], v[230:233], v[2:5]
	s_setprio 0
	s_barrier
	s_add_u32 s26, s26, 0x100
	s_addc_u32 s27, s27, 0
	s_add_u32 s53, s53, 0x100
	s_addc_u32 s54, s54, 0
	s_cmp_ge_i32 s55, s45
	s_mov_b32 s28, s55
	s_cbranch_scc0 .LBB0_1864
